# NSA loop: S tile no longer copied (16 v_mov_b64 per step removed): the two S register sets alternate roles per step, 3-step body unrolled to 6
# speedup vs baseline: 1.0041x; 1.0032x over previous
; #define LAS __attribute__((address_space(3)))
; DI float sigmoidf_(float x) { return __builtin_amdgcn_rcpf(1.0f + __expf(-x)); }
; #define MFMA32(a, b, c) __builtin_amdgcn_mfma_f32_32x32x16_bf16((a), (b), (c), 0, 0, 0)
; DI void fs_reset(FState& st) { st.o0 = f16zero(); st.o1 = f16zero(); st.m = NINF; st.l = 0.f; }
; DI void flash_qk(const LAS unsigned char* kb, const bf16x8 (&qf)[4], f32x16& p0, f32x16& p1, int r32, int h) {
;     p0 = f16zero(); p1 = f16zero();
;     const int sw = (r32 >> 1) & 7;
; #pragma unroll
;     for (int s = 0; s < 4; ++s) {
;         const int off = r32 * 128 + (((2 * s + h) ^ sw) << 4);
;         const bf16x8 a0 = *(const LAS bf16x8*)(kb + off), a1 = *(const LAS bf16x8*)(kb + off + 4096);
;         p0 = MFMA32(a0, qf[s], p0); p1 = MFMA32(a1, qf[s], p1);
;     }
; DI void nsa_task(LAS unsigned char* lds, const bf16_t* Z, const unsigned* selm, const bf16_t* OCMP, bf16_t* YA, int b, int hk, int c, int tid, int wave, int lane) {
;     ...
;     const float g_cmp = sigmoidf_(bf2f(zr[ZC_GA + head])), g_slc = sigmoidf_(bf2f(zr[ZC_GA + 8 + head])), g_win = sigmoidf_(bf2f(zr[ZC_GA + 16 + head]));
;     f32x16 y0 = f16zero(), y1 = f16zero();
;     FState st; fs_reset(st);
;     const int nsel = EN_SLC ? c + 1 : 0, nwin = EN_WIN ? (c + 1 < 9 ? c + 1 : 9) : 0, ntot = nsel + nwin;
;     const int skey = tid >> 3, sch = tid & 7;
;     const int kdst = skey * 128 + ((sch ^ ((skey >> 1) & 7)) << 4), vdst = 8192 + skey * 128 + ((sch * 16) ^ (((skey >> 1) & 1) << 6));
;     const bf16_t* sbase = Z + ((size_t)b * SEQ + skey) * NZ + hk * 64 + sch * 8;
;     u32x4 kA = {0u, 0u, 0u, 0u}, vA = kA, kB = kA, vB = kA, kC = kA, vC = kA;
.LBB0_740:
	s_waitcnt vmcnt(3)
	v_lshlrev_b32_e32 v5, 16, v5
	v_mul_f32_e32 v5, 0xbfb8aa3b, v5
	v_exp_f32_e32 v5, v5
	v_lshlrev_b32_e32 v195, 6, v4
	v_lshlrev_b32_e32 v4, 7, v194
	v_lshlrev_b32_e32 v6, 4, v205
	v_add_f32_e32 v5, 1.0, v5
	v_rcp_f32_e32 v197, v5
	v_lshlrev_b32_e32 v5, 6, v206
	v_and_b32_e32 v5, 64, v5
	v_mov_b32_e32 v16, v3
	v_mov_b32_e32 v17, v3
	v_and_or_b32 v205, v6, s66, v4
	v_lshlrev_b32_e32 v206, 4, v207
	v_lshlrev_b32_e32 v207, 4, v208
	v_lshlrev_b32_e32 v208, 4, v209
	v_lshlrev_b32_e32 v209, 4, v212
	s_add_i32 s4, s50, s69
	v_bitop3_b32 v212, v5, v4, v2 bitop3:0xde
	v_mov_b32_e32 v2, v3
	v_mov_b32_e32 v4, v3
	v_mov_b32_e32 v5, v3
	v_mov_b32_e32 v6, v3
	v_mov_b32_e32 v7, v3
	v_mov_b32_e32 v8, v3
	v_mov_b32_e32 v9, v3
	v_mov_b32_e32 v10, v3
	v_mov_b32_e32 v11, v3
	v_mov_b32_e32 v12, v3
	v_mov_b32_e32 v13, v3
	v_mov_b32_e32 v14, v3
	v_mov_b32_e32 v15, v3
	v_mov_b64_e32 v[80:81], v[16:17]
	v_mov_b64_e32 v[64:65], v[16:17]
	v_mov_b64_e32 v[48:49], v[16:17]
	v_mov_b64_e32 v[32:33], v[16:17]
	v_lshlrev_b32_e32 v194, 2, v210
	v_add_u32_e32 v210, 0xfffffe00, v190
	v_lshlrev_b32_e32 v211, 7, v211
	s_add_i32 s52, s4, -5
	s_mov_b32 s53, 0
	v_sub_u32_e32 v213, 0, v202
	s_sub_i32 s70, 0, s69
	s_add_i32 s71, s69, -2
	s_add_i32 s72, s69, -1
	v_mov_b32_e32 v214, 0
	v_mov_b32_e32 v216, 0xff800000
	s_mov_b32 s74, 0
	v_mov_b64_e32 v[78:79], v[14:15]
	v_mov_b64_e32 v[76:77], v[12:13]
	v_mov_b64_e32 v[74:75], v[10:11]
	v_mov_b64_e32 v[72:73], v[8:9]
	v_mov_b64_e32 v[70:71], v[6:7]
	v_mov_b64_e32 v[68:69], v[4:5]
	v_mov_b64_e32 v[66:67], v[2:3]
	v_mov_b64_e32 v[62:63], v[14:15]
	v_mov_b64_e32 v[60:61], v[12:13]
	v_mov_b64_e32 v[58:59], v[10:11]
	v_mov_b64_e32 v[56:57], v[8:9]
	v_mov_b64_e32 v[54:55], v[6:7]
	v_mov_b64_e32 v[52:53], v[4:5]
	v_mov_b64_e32 v[50:51], v[2:3]
	v_mov_b64_e32 v[46:47], v[14:15]
	v_mov_b64_e32 v[44:45], v[12:13]
	v_mov_b64_e32 v[42:43], v[10:11]
	v_mov_b64_e32 v[40:41], v[8:9]
	v_mov_b64_e32 v[38:39], v[6:7]
	v_mov_b64_e32 v[36:37], v[4:5]
	v_mov_b64_e32 v[34:35], v[2:3]
	v_mov_b64_e32 v[30:31], v[14:15]
	v_mov_b64_e32 v[28:29], v[12:13]
	v_mov_b64_e32 v[26:27], v[10:11]
	v_mov_b64_e32 v[24:25], v[8:9]
	v_mov_b64_e32 v[22:23], v[6:7]
	v_mov_b64_e32 v[20:21], v[4:5]
	v_mov_b64_e32 v[18:19], v[2:3]
	ds_write_b128 v205, v[162:165]
	ds_write_b128 v212, v[166:169] offset:8192
	v_add_u32_e32 v221, v201, v206
	v_add_u32_e32 v222, v201, v207
	v_add_u32_e32 v223, v201, v208
	v_add_u32_e32 v224, v201, v209
	s_waitcnt lgkmcnt(0)
	s_barrier
	ds_read_b128 v[226:229], v221
	ds_read_b128 v[230:233], v221 offset:4096
	ds_read_b128 v[234:237], v222
	ds_read_b128 v[238:241], v222 offset:4096
	s_waitcnt lgkmcnt(3)
	v_mfma_f32_32x32x16_bf16 v[98:113], v[226:229], v[146:149], 0
	s_waitcnt lgkmcnt(2)
	v_mfma_f32_32x32x16_bf16 v[82:97], v[230:233], v[146:149], 0
	ds_read_b128 v[226:229], v223
	ds_read_b128 v[230:233], v223 offset:4096
	s_waitcnt lgkmcnt(3)
	v_mfma_f32_32x32x16_bf16 v[98:113], v[234:237], v[150:153], v[98:113]
	s_waitcnt lgkmcnt(2)
	v_mfma_f32_32x32x16_bf16 v[82:97], v[238:241], v[150:153], v[82:97]
	ds_read_b128 v[234:237], v224
	ds_read_b128 v[238:241], v224 offset:4096
	s_waitcnt lgkmcnt(3)
	v_mfma_f32_32x32x16_bf16 v[98:113], v[226:229], v[154:157], v[98:113]
	s_waitcnt lgkmcnt(2)
	v_mfma_f32_32x32x16_bf16 v[82:97], v[230:233], v[154:157], v[82:97]
	s_waitcnt lgkmcnt(1)
	v_mfma_f32_32x32x16_bf16 v[98:113], v[234:237], v[158:161], v[98:113]
	s_waitcnt lgkmcnt(0)
	v_mfma_f32_32x32x16_bf16 v[82:97], v[238:241], v[158:161], v[82:97]

.LBB0_745:
	s_add_i32 s10, s52, 5
	s_cmp_gt_u32 s74, s69
	s_cselect_b64 s[8:9], -1, 0
	s_and_b64 vcc, s[8:9], exec
	s_cselect_b32 s8, s10, s74
	v_lshl_or_b32 v2, s8, 6, v194
	s_mov_b64 s[10:11], -1
	s_cbranch_vccnz .LBB0_749
	v_lshrrev_b32_e32 v4, s74, v196
	v_and_b32_e32 v4, 1, v4
	v_cmp_eq_u32_e64 s[8:9], 1, v4
	s_cmp_lg_u32 s69, s74
	s_cbranch_scc1 .LBB0_748
	v_cmp_le_i32_e32 vcc, v2, v190
	v_or_b32_e32 v4, 32, v2
	s_nop 0
	v_cndmask_b32_e32 v98, v186, v98, vcc
	v_cmp_le_i32_e32 vcc, v4, v190
	v_or_b32_e32 v4, 33, v2
	s_nop 0
	v_cndmask_b32_e32 v82, v186, v82, vcc
	v_cmp_lt_i32_e32 vcc, v2, v190
	s_nop 1
	v_cndmask_b32_e32 v99, v186, v99, vcc
	v_cmp_le_i32_e32 vcc, v4, v190
	v_or_b32_e32 v4, 2, v2
	s_nop 0
	v_cndmask_b32_e32 v83, v186, v83, vcc
	v_cmp_le_i32_e32 vcc, v4, v190
	v_or_b32_e32 v4, 34, v2
	s_nop 0
	v_cndmask_b32_e32 v100, v186, v100, vcc
	v_cmp_le_i32_e32 vcc, v4, v190
	v_or_b32_e32 v4, 3, v2
	s_nop 0
	v_cndmask_b32_e32 v84, v186, v84, vcc
	v_cmp_le_i32_e32 vcc, v4, v190
	v_or_b32_e32 v4, 35, v2
	s_nop 0
	v_cndmask_b32_e32 v101, v186, v101, vcc
	v_cmp_le_i32_e32 vcc, v4, v190
	v_or_b32_e32 v4, 8, v2
	s_nop 0
	v_cndmask_b32_e32 v85, v186, v85, vcc
	v_cmp_le_i32_e32 vcc, v4, v190
	v_or_b32_e32 v4, 40, v2
	s_nop 0
	v_cndmask_b32_e32 v102, v186, v102, vcc
	v_cmp_le_i32_e32 vcc, v4, v190
	v_or_b32_e32 v4, 9, v2
	s_nop 0
	v_cndmask_b32_e32 v86, v186, v86, vcc
	v_cmp_le_i32_e32 vcc, v4, v190
	v_or_b32_e32 v4, 41, v2
	s_nop 0
	v_cndmask_b32_e32 v103, v186, v103, vcc
	v_cmp_le_i32_e32 vcc, v4, v190
	v_or_b32_e32 v4, 10, v2
	s_nop 0
	v_cndmask_b32_e32 v87, v186, v87, vcc
	v_cmp_le_i32_e32 vcc, v4, v190
	v_or_b32_e32 v4, 42, v2
	s_nop 0
	v_cndmask_b32_e32 v104, v186, v104, vcc
	v_cmp_le_i32_e32 vcc, v4, v190
	v_or_b32_e32 v4, 11, v2
	s_nop 0
	v_cndmask_b32_e32 v88, v186, v88, vcc
	v_cmp_le_i32_e32 vcc, v4, v190
	v_or_b32_e32 v4, 43, v2
	s_nop 0
	v_cndmask_b32_e32 v105, v186, v105, vcc
	v_cmp_le_i32_e32 vcc, v4, v190
	v_or_b32_e32 v4, 16, v2
	s_nop 0
	v_cndmask_b32_e32 v89, v186, v89, vcc
	v_cmp_le_i32_e32 vcc, v4, v190
	v_or_b32_e32 v4, 48, v2
	s_nop 0
	v_cndmask_b32_e32 v106, v186, v106, vcc
	v_cmp_le_i32_e32 vcc, v4, v190
	v_or_b32_e32 v4, 17, v2
	s_nop 0
	v_cndmask_b32_e32 v90, v186, v90, vcc
	v_cmp_le_i32_e32 vcc, v4, v190
	v_or_b32_e32 v4, 49, v2
	s_nop 0
	v_cndmask_b32_e32 v107, v186, v107, vcc
	v_cmp_le_i32_e32 vcc, v4, v190
	v_or_b32_e32 v4, 18, v2
	s_nop 0
	v_cndmask_b32_e32 v91, v186, v91, vcc
	v_cmp_le_i32_e32 vcc, v4, v190
	v_or_b32_e32 v4, 50, v2
	s_nop 0
	v_cndmask_b32_e32 v108, v186, v108, vcc
	v_cmp_le_i32_e32 vcc, v4, v190
	v_or_b32_e32 v4, 19, v2
	s_nop 0
	v_cndmask_b32_e32 v92, v186, v92, vcc
	v_cmp_le_i32_e32 vcc, v4, v190
	v_or_b32_e32 v4, 51, v2
	s_nop 0
	v_cndmask_b32_e32 v109, v186, v109, vcc
	v_cmp_le_i32_e32 vcc, v4, v190
	v_or_b32_e32 v4, 24, v2
	s_nop 0
	v_cndmask_b32_e32 v93, v186, v93, vcc
	v_cmp_le_i32_e32 vcc, v4, v190
	v_or_b32_e32 v4, 56, v2
	s_nop 0
	v_cndmask_b32_e32 v110, v186, v110, vcc
	v_cmp_le_i32_e32 vcc, v4, v190
	v_or_b32_e32 v4, 25, v2
	s_nop 0
	v_cndmask_b32_e32 v94, v186, v94, vcc
	v_cmp_le_i32_e32 vcc, v4, v190
	v_or_b32_e32 v4, 57, v2
	s_nop 0
	v_cndmask_b32_e32 v111, v186, v111, vcc
	v_cmp_le_i32_e32 vcc, v4, v190
	v_or_b32_e32 v4, 26, v2
	s_nop 0
	v_cndmask_b32_e32 v95, v186, v95, vcc
	v_cmp_le_i32_e32 vcc, v4, v190
	v_or_b32_e32 v4, 58, v2
	s_nop 0
	v_cndmask_b32_e32 v112, v186, v112, vcc
	v_cmp_le_i32_e32 vcc, v4, v190
	v_or_b32_e32 v4, 27, v2
	s_nop 0
	v_cndmask_b32_e32 v96, v186, v96, vcc
	v_cmp_le_i32_e32 vcc, v4, v190
	v_or_b32_e32 v4, 59, v2
	s_nop 0
	v_cndmask_b32_e32 v113, v186, v113, vcc
	v_cmp_le_i32_e32 vcc, v4, v190
	s_nop 1
	v_cndmask_b32_e32 v97, v186, v97, vcc

.LBB0_749:
	s_andn2_b64 vcc, exec, s[10:11]
	s_add_i32 s75, s70, s74
	s_cbranch_vccnz .LBB0_753
	s_cmp_eq_u32 s75, 9
	s_cselect_b64 s[8:9], -1, 0
	s_or_b64 s[4:5], s[4:5], s[8:9]
	s_andn2_b64 vcc, exec, s[4:5]
	s_cbranch_vccnz .LBB0_752
	v_cmp_le_i32_e32 vcc, v2, v190
	v_cmp_gt_i32_e64 s[4:5], v2, v210
	s_and_b64 vcc, vcc, s[4:5]
	v_or_b32_e32 v4, 32, v2
	v_cndmask_b32_e32 v98, v186, v98, vcc
	v_cmp_le_i32_e32 vcc, v4, v190
	v_cmp_gt_i32_e64 s[4:5], v4, v210
	s_and_b64 vcc, vcc, s[4:5]
	v_cndmask_b32_e32 v82, v186, v82, vcc
	v_cmp_lt_i32_e32 vcc, v2, v190
	v_cmp_ge_i32_e64 s[4:5], v2, v210
	s_and_b64 vcc, vcc, s[4:5]
	v_or_b32_e32 v4, 33, v2
	v_cndmask_b32_e32 v99, v186, v99, vcc
	v_cmp_le_i32_e32 vcc, v4, v190
	v_cmp_gt_i32_e64 s[4:5], v4, v210
	s_and_b64 vcc, vcc, s[4:5]
	v_or_b32_e32 v4, 2, v2
	v_cndmask_b32_e32 v83, v186, v83, vcc
	v_cmp_le_i32_e32 vcc, v4, v190
	v_cmp_gt_i32_e64 s[4:5], v4, v210
	s_and_b64 vcc, vcc, s[4:5]
	v_or_b32_e32 v4, 34, v2
	v_cndmask_b32_e32 v100, v186, v100, vcc
	v_cmp_le_i32_e32 vcc, v4, v190
	v_cmp_gt_i32_e64 s[4:5], v4, v210
	s_and_b64 vcc, vcc, s[4:5]
	v_or_b32_e32 v4, 3, v2
	v_cndmask_b32_e32 v84, v186, v84, vcc
	v_cmp_le_i32_e32 vcc, v4, v190
	v_cmp_gt_i32_e64 s[4:5], v4, v210
	s_and_b64 vcc, vcc, s[4:5]
	v_or_b32_e32 v4, 35, v2
	v_cndmask_b32_e32 v101, v186, v101, vcc
	v_cmp_le_i32_e32 vcc, v4, v190
	v_cmp_gt_i32_e64 s[4:5], v4, v210
	s_and_b64 vcc, vcc, s[4:5]
	v_or_b32_e32 v4, 8, v2
	v_cndmask_b32_e32 v85, v186, v85, vcc
	v_cmp_le_i32_e32 vcc, v4, v190
	v_cmp_gt_i32_e64 s[4:5], v4, v210
	s_and_b64 vcc, vcc, s[4:5]
	v_or_b32_e32 v4, 40, v2
	v_cndmask_b32_e32 v102, v186, v102, vcc
	v_cmp_le_i32_e32 vcc, v4, v190
	v_cmp_gt_i32_e64 s[4:5], v4, v210
	s_and_b64 vcc, vcc, s[4:5]
	v_or_b32_e32 v4, 9, v2
	v_cndmask_b32_e32 v86, v186, v86, vcc
	v_cmp_le_i32_e32 vcc, v4, v190
	v_cmp_gt_i32_e64 s[4:5], v4, v210
	s_and_b64 vcc, vcc, s[4:5]
	v_or_b32_e32 v4, 41, v2
	v_cndmask_b32_e32 v103, v186, v103, vcc
	v_cmp_le_i32_e32 vcc, v4, v190
	v_cmp_gt_i32_e64 s[4:5], v4, v210
	s_and_b64 vcc, vcc, s[4:5]
	v_or_b32_e32 v4, 10, v2
	v_cndmask_b32_e32 v87, v186, v87, vcc
	v_cmp_le_i32_e32 vcc, v4, v190
	v_cmp_gt_i32_e64 s[4:5], v4, v210
	s_and_b64 vcc, vcc, s[4:5]
	v_or_b32_e32 v4, 42, v2
	v_cndmask_b32_e32 v104, v186, v104, vcc
	v_cmp_le_i32_e32 vcc, v4, v190
	v_cmp_gt_i32_e64 s[4:5], v4, v210
	s_and_b64 vcc, vcc, s[4:5]
	v_or_b32_e32 v4, 11, v2
	v_cndmask_b32_e32 v88, v186, v88, vcc
	v_cmp_le_i32_e32 vcc, v4, v190
	v_cmp_gt_i32_e64 s[4:5], v4, v210
	s_and_b64 vcc, vcc, s[4:5]
	v_or_b32_e32 v4, 43, v2
	v_cndmask_b32_e32 v105, v186, v105, vcc
	v_cmp_le_i32_e32 vcc, v4, v190
	v_cmp_gt_i32_e64 s[4:5], v4, v210
	s_and_b64 vcc, vcc, s[4:5]
	v_or_b32_e32 v4, 16, v2
	v_cndmask_b32_e32 v89, v186, v89, vcc
	v_cmp_le_i32_e32 vcc, v4, v190
	v_cmp_gt_i32_e64 s[4:5], v4, v210
	s_and_b64 vcc, vcc, s[4:5]
	v_or_b32_e32 v4, 48, v2
	v_cndmask_b32_e32 v106, v186, v106, vcc
	v_cmp_le_i32_e32 vcc, v4, v190
	v_cmp_gt_i32_e64 s[4:5], v4, v210
	s_and_b64 vcc, vcc, s[4:5]
	v_or_b32_e32 v4, 17, v2
	v_cndmask_b32_e32 v90, v186, v90, vcc
	v_cmp_le_i32_e32 vcc, v4, v190
	v_cmp_gt_i32_e64 s[4:5], v4, v210
	s_and_b64 vcc, vcc, s[4:5]
	v_or_b32_e32 v4, 49, v2
	v_cndmask_b32_e32 v107, v186, v107, vcc
	v_cmp_le_i32_e32 vcc, v4, v190
	v_cmp_gt_i32_e64 s[4:5], v4, v210
	s_and_b64 vcc, vcc, s[4:5]
	v_or_b32_e32 v4, 18, v2
	v_cndmask_b32_e32 v91, v186, v91, vcc
	v_cmp_le_i32_e32 vcc, v4, v190
	v_cmp_gt_i32_e64 s[4:5], v4, v210
	s_and_b64 vcc, vcc, s[4:5]
	v_or_b32_e32 v4, 50, v2
	v_cndmask_b32_e32 v108, v186, v108, vcc
	v_cmp_le_i32_e32 vcc, v4, v190
	v_cmp_gt_i32_e64 s[4:5], v4, v210
	s_and_b64 vcc, vcc, s[4:5]
	v_or_b32_e32 v4, 19, v2
	v_cndmask_b32_e32 v92, v186, v92, vcc
	v_cmp_le_i32_e32 vcc, v4, v190
	v_cmp_gt_i32_e64 s[4:5], v4, v210
	s_and_b64 vcc, vcc, s[4:5]
	v_or_b32_e32 v4, 51, v2
	v_cndmask_b32_e32 v109, v186, v109, vcc
	v_cmp_le_i32_e32 vcc, v4, v190
	v_cmp_gt_i32_e64 s[4:5], v4, v210
	s_and_b64 vcc, vcc, s[4:5]
	v_or_b32_e32 v4, 24, v2
	v_cndmask_b32_e32 v93, v186, v93, vcc
	v_cmp_le_i32_e32 vcc, v4, v190
	v_cmp_gt_i32_e64 s[4:5], v4, v210
	s_and_b64 vcc, vcc, s[4:5]
	v_or_b32_e32 v4, 56, v2
	v_cndmask_b32_e32 v110, v186, v110, vcc
	v_cmp_le_i32_e32 vcc, v4, v190
	v_cmp_gt_i32_e64 s[4:5], v4, v210
	s_and_b64 vcc, vcc, s[4:5]
	v_or_b32_e32 v4, 25, v2
	v_cndmask_b32_e32 v94, v186, v94, vcc
	v_cmp_le_i32_e32 vcc, v4, v190
	v_cmp_gt_i32_e64 s[4:5], v4, v210
	s_and_b64 vcc, vcc, s[4:5]
	v_or_b32_e32 v4, 57, v2
	v_cndmask_b32_e32 v111, v186, v111, vcc
	v_cmp_le_i32_e32 vcc, v4, v190
	v_cmp_gt_i32_e64 s[4:5], v4, v210
	s_and_b64 vcc, vcc, s[4:5]
	v_or_b32_e32 v4, 26, v2
	v_cndmask_b32_e32 v95, v186, v95, vcc
	v_cmp_le_i32_e32 vcc, v4, v190
	v_cmp_gt_i32_e64 s[4:5], v4, v210
	s_and_b64 vcc, vcc, s[4:5]
	v_or_b32_e32 v4, 58, v2
	v_cndmask_b32_e32 v112, v186, v112, vcc
	v_cmp_le_i32_e32 vcc, v4, v190
	v_cmp_gt_i32_e64 s[4:5], v4, v210
	s_and_b64 vcc, vcc, s[4:5]
	v_or_b32_e32 v4, 27, v2
	v_cndmask_b32_e32 v96, v186, v96, vcc
	v_cmp_le_i32_e32 vcc, v4, v190
	v_cmp_gt_i32_e64 s[4:5], v4, v210
	s_and_b64 vcc, vcc, s[4:5]
	v_or_b32_e32 v2, 59, v2
	v_cndmask_b32_e32 v113, v186, v113, vcc
	v_cmp_le_i32_e32 vcc, v2, v190
	v_cmp_gt_i32_e64 s[4:5], v2, v210
	s_and_b64 vcc, vcc, s[4:5]
	v_cndmask_b32_e32 v97, v186, v97, vcc
.LBB0_752:
	s_nop 0
	s_nop 0
	s_mov_b64 s[8:9], -1

.LBB0_764:
	s_add_i32 s8, s52, 4
	s_cmp_lt_u32 s74, s69
	s_cselect_b32 s8, s77, s8
	s_cmp_ge_u32 s74, s69
	s_mov_b64 s[10:11], -1
	v_lshl_or_b32 v2, s8, 6, v194
	s_mov_b64 s[8:9], -1
	s_cbranch_scc0 .LBB0_768
	s_cmp_eq_u32 s75, 8
	s_cselect_b64 s[10:11], -1, 0
	s_or_b64 s[4:5], s[4:5], s[10:11]
	s_andn2_b64 vcc, exec, s[4:5]
	s_cbranch_vccnz .LBB0_767
	v_cmp_le_i32_e32 vcc, v2, v190
	v_cmp_gt_i32_e64 s[4:5], v2, v210
	s_and_b64 vcc, vcc, s[4:5]
	v_or_b32_e32 v4, 32, v2
	v_cndmask_b32_e32 v130, v186, v130, vcc
	v_cmp_le_i32_e32 vcc, v4, v190
	v_cmp_gt_i32_e64 s[4:5], v4, v210
	s_and_b64 vcc, vcc, s[4:5]
	v_cndmask_b32_e32 v114, v186, v114, vcc
	v_cmp_lt_i32_e32 vcc, v2, v190
	v_cmp_ge_i32_e64 s[4:5], v2, v210
	s_and_b64 vcc, vcc, s[4:5]
	v_or_b32_e32 v4, 33, v2
	v_cndmask_b32_e32 v131, v186, v131, vcc
	v_cmp_le_i32_e32 vcc, v4, v190
	v_cmp_gt_i32_e64 s[4:5], v4, v210
	s_and_b64 vcc, vcc, s[4:5]
	v_or_b32_e32 v4, 2, v2
	v_cndmask_b32_e32 v115, v186, v115, vcc
	v_cmp_le_i32_e32 vcc, v4, v190
	v_cmp_gt_i32_e64 s[4:5], v4, v210
	s_and_b64 vcc, vcc, s[4:5]
	v_or_b32_e32 v4, 34, v2
	v_cndmask_b32_e32 v132, v186, v132, vcc
	v_cmp_le_i32_e32 vcc, v4, v190
	v_cmp_gt_i32_e64 s[4:5], v4, v210
	s_and_b64 vcc, vcc, s[4:5]
	v_or_b32_e32 v4, 3, v2
	v_cndmask_b32_e32 v116, v186, v116, vcc
	v_cmp_le_i32_e32 vcc, v4, v190
	v_cmp_gt_i32_e64 s[4:5], v4, v210
	s_and_b64 vcc, vcc, s[4:5]
	v_or_b32_e32 v4, 35, v2
	v_cndmask_b32_e32 v133, v186, v133, vcc
	v_cmp_le_i32_e32 vcc, v4, v190
	v_cmp_gt_i32_e64 s[4:5], v4, v210
	s_and_b64 vcc, vcc, s[4:5]
	v_or_b32_e32 v4, 8, v2
	v_cndmask_b32_e32 v117, v186, v117, vcc
	v_cmp_le_i32_e32 vcc, v4, v190
	v_cmp_gt_i32_e64 s[4:5], v4, v210
	s_and_b64 vcc, vcc, s[4:5]
	v_or_b32_e32 v4, 40, v2
	v_cndmask_b32_e32 v134, v186, v134, vcc
	v_cmp_le_i32_e32 vcc, v4, v190
	v_cmp_gt_i32_e64 s[4:5], v4, v210
	s_and_b64 vcc, vcc, s[4:5]
	v_or_b32_e32 v4, 9, v2
	v_cndmask_b32_e32 v118, v186, v118, vcc
	v_cmp_le_i32_e32 vcc, v4, v190
	v_cmp_gt_i32_e64 s[4:5], v4, v210
	s_and_b64 vcc, vcc, s[4:5]
	v_or_b32_e32 v4, 41, v2
	v_cndmask_b32_e32 v135, v186, v135, vcc
	v_cmp_le_i32_e32 vcc, v4, v190
	v_cmp_gt_i32_e64 s[4:5], v4, v210
	s_and_b64 vcc, vcc, s[4:5]
	v_or_b32_e32 v4, 10, v2
	v_cndmask_b32_e32 v119, v186, v119, vcc
	v_cmp_le_i32_e32 vcc, v4, v190
	v_cmp_gt_i32_e64 s[4:5], v4, v210
	s_and_b64 vcc, vcc, s[4:5]
	v_or_b32_e32 v4, 42, v2
	v_cndmask_b32_e32 v136, v186, v136, vcc
	v_cmp_le_i32_e32 vcc, v4, v190
	v_cmp_gt_i32_e64 s[4:5], v4, v210
	s_and_b64 vcc, vcc, s[4:5]
	v_or_b32_e32 v4, 11, v2
	v_cndmask_b32_e32 v120, v186, v120, vcc
	v_cmp_le_i32_e32 vcc, v4, v190
	v_cmp_gt_i32_e64 s[4:5], v4, v210
	s_and_b64 vcc, vcc, s[4:5]
	v_or_b32_e32 v4, 43, v2
	v_cndmask_b32_e32 v137, v186, v137, vcc
	v_cmp_le_i32_e32 vcc, v4, v190
	v_cmp_gt_i32_e64 s[4:5], v4, v210
	s_and_b64 vcc, vcc, s[4:5]
	v_or_b32_e32 v4, 16, v2
	v_cndmask_b32_e32 v121, v186, v121, vcc
	v_cmp_le_i32_e32 vcc, v4, v190
	v_cmp_gt_i32_e64 s[4:5], v4, v210
	s_and_b64 vcc, vcc, s[4:5]
	v_or_b32_e32 v4, 48, v2
	v_cndmask_b32_e32 v138, v186, v138, vcc
	v_cmp_le_i32_e32 vcc, v4, v190
	v_cmp_gt_i32_e64 s[4:5], v4, v210
	s_and_b64 vcc, vcc, s[4:5]
	v_or_b32_e32 v4, 17, v2
	v_cndmask_b32_e32 v122, v186, v122, vcc
	v_cmp_le_i32_e32 vcc, v4, v190
	v_cmp_gt_i32_e64 s[4:5], v4, v210
	s_and_b64 vcc, vcc, s[4:5]
	v_or_b32_e32 v4, 49, v2
	v_cndmask_b32_e32 v139, v186, v139, vcc
	v_cmp_le_i32_e32 vcc, v4, v190
	v_cmp_gt_i32_e64 s[4:5], v4, v210
	s_and_b64 vcc, vcc, s[4:5]
	v_or_b32_e32 v4, 18, v2
	v_cndmask_b32_e32 v123, v186, v123, vcc
	v_cmp_le_i32_e32 vcc, v4, v190
	v_cmp_gt_i32_e64 s[4:5], v4, v210
	s_and_b64 vcc, vcc, s[4:5]
	v_or_b32_e32 v4, 50, v2
	v_cndmask_b32_e32 v140, v186, v140, vcc
	v_cmp_le_i32_e32 vcc, v4, v190
	v_cmp_gt_i32_e64 s[4:5], v4, v210
	s_and_b64 vcc, vcc, s[4:5]
	v_or_b32_e32 v4, 19, v2
	v_cndmask_b32_e32 v124, v186, v124, vcc
	v_cmp_le_i32_e32 vcc, v4, v190
	v_cmp_gt_i32_e64 s[4:5], v4, v210
	s_and_b64 vcc, vcc, s[4:5]
	v_or_b32_e32 v4, 51, v2
	v_cndmask_b32_e32 v141, v186, v141, vcc
	v_cmp_le_i32_e32 vcc, v4, v190
	v_cmp_gt_i32_e64 s[4:5], v4, v210
	s_and_b64 vcc, vcc, s[4:5]
	v_or_b32_e32 v4, 24, v2
	v_cndmask_b32_e32 v125, v186, v125, vcc
	v_cmp_le_i32_e32 vcc, v4, v190
	v_cmp_gt_i32_e64 s[4:5], v4, v210
	s_and_b64 vcc, vcc, s[4:5]
	v_or_b32_e32 v4, 56, v2
	v_cndmask_b32_e32 v142, v186, v142, vcc
	v_cmp_le_i32_e32 vcc, v4, v190
	v_cmp_gt_i32_e64 s[4:5], v4, v210
	s_and_b64 vcc, vcc, s[4:5]
	v_or_b32_e32 v4, 25, v2
	v_cndmask_b32_e32 v126, v186, v126, vcc
	v_cmp_le_i32_e32 vcc, v4, v190
	v_cmp_gt_i32_e64 s[4:5], v4, v210
	s_and_b64 vcc, vcc, s[4:5]
	v_or_b32_e32 v4, 57, v2
	v_cndmask_b32_e32 v143, v186, v143, vcc
	v_cmp_le_i32_e32 vcc, v4, v190
	v_cmp_gt_i32_e64 s[4:5], v4, v210
	s_and_b64 vcc, vcc, s[4:5]
	v_or_b32_e32 v4, 26, v2
	v_cndmask_b32_e32 v127, v186, v127, vcc
	v_cmp_le_i32_e32 vcc, v4, v190
	v_cmp_gt_i32_e64 s[4:5], v4, v210
	s_and_b64 vcc, vcc, s[4:5]
	v_or_b32_e32 v4, 58, v2
	v_cndmask_b32_e32 v144, v186, v144, vcc
	v_cmp_le_i32_e32 vcc, v4, v190
	v_cmp_gt_i32_e64 s[4:5], v4, v210
	s_and_b64 vcc, vcc, s[4:5]
	v_or_b32_e32 v4, 27, v2
	v_cndmask_b32_e32 v128, v186, v128, vcc
	v_cmp_le_i32_e32 vcc, v4, v190
	v_cmp_gt_i32_e64 s[4:5], v4, v210
	s_and_b64 vcc, vcc, s[4:5]
	v_or_b32_e32 v4, 59, v2
	v_cndmask_b32_e32 v145, v186, v145, vcc
	v_cmp_le_i32_e32 vcc, v4, v190
	v_cmp_gt_i32_e64 s[4:5], v4, v210
	s_and_b64 vcc, vcc, s[4:5]
	v_cndmask_b32_e32 v129, v186, v129, vcc

; #define LAS __attribute__((address_space(3)))
; #define MFMA32(a, b, c) __builtin_amdgcn_mfma_f32_32x32x16_bf16((a), (b), (c), 0, 0, 0)
; DI float fexp2(float x) { return __builtin_amdgcn_exp2f(x); }
; DI float half_max(float v) { return fmaxf(v, __shfl_xor(v, 32)); }
; DI void flash_qk(const LAS unsigned char* kb, const bf16x8 (&qf)[4], f32x16& p0, f32x16& p1, int r32, int h) {
;     p0 = f16zero(); p1 = f16zero();
;     const int sw = (r32 >> 1) & 7;
; #pragma unroll
;     for (int s = 0; s < 4; ++s) {
;         const int off = r32 * 128 + (((2 * s + h) ^ sw) << 4);
;         const bf16x8 a0 = *(const LAS bf16x8*)(kb + off), a1 = *(const LAS bf16x8*)(kb + off + 4096);
;         p0 = MFMA32(a0, qf[s], p0); p1 = MFMA32(a1, qf[s], p1);
;     }
; DI void flash_pv(FState& st, f32x16& p0, f32x16& p1, bool rowon, const LAS unsigned char* vb, int lane) {
;     float mx = fmaxf(p0[0], p1[0]);
; #pragma unroll
;     for (int r = 1; r < 16; ++r) asm("v_max3_f32 %0, %1, %2, %3" : "=v"(mx) : "v"(mx), "v"(p0[r]), "v"(p1[r]));
;     mx = half_max(mx);
;     mx = rowon ? mx : NINF;
;     const bool upd = mx > st.m + THR_RAW;
;     if (__any(upd)) {
;         const float mn = upd ? mx : st.m;
;         const float alpha = upd ? fexp2((st.m - mn) * SM_C) : 1.0f;
;         st.m = mn; st.l *= alpha;
; #pragma unroll
;         for (int r = 0; r < 16; ++r) { st.o0[r] *= alpha; st.o1[r] *= alpha; }
;     }
.LBB0_771:
	s_nop 1
	s_nop 0
.LBB0_772:
	v_max_f32_e32 v2, v114, v114
	v_max_f32_e32 v4, v130, v130
	v_max_f32_e32 v2, v4, v2
	s_waitcnt lgkmcnt(3)
	v_mfma_f32_32x32x16_bf16 v[98:113], v[226:229], v[146:149], 0
	v_max3_f32 v2, v2, v131, v115
	v_max3_f32 v2, v2, v132, v116
	v_max3_f32 v2, v2, v133, v117
	v_max3_f32 v2, v2, v134, v118
	s_waitcnt lgkmcnt(2)
	v_mfma_f32_32x32x16_bf16 v[82:97], v[230:233], v[146:149], 0
	ds_read_b128 v[226:229], v223 offset:32768
	ds_read_b128 v[230:233], v223 offset:36864
	v_max3_f32 v2, v2, v135, v119
	v_max3_f32 v2, v2, v136, v120
	v_max3_f32 v2, v2, v137, v121
	v_max3_f32 v2, v2, v138, v122
	s_waitcnt lgkmcnt(3)
	v_mfma_f32_32x32x16_bf16 v[98:113], v[234:237], v[150:153], v[98:113]
	v_max3_f32 v2, v2, v139, v123
	v_max3_f32 v2, v2, v140, v124
	v_max3_f32 v2, v2, v141, v125
	v_max3_f32 v2, v2, v142, v126
	s_waitcnt lgkmcnt(2)
	v_mfma_f32_32x32x16_bf16 v[82:97], v[238:241], v[150:153], v[82:97]
	ds_read_b128 v[234:237], v224 offset:32768
	ds_read_b128 v[238:241], v224 offset:36864
	v_max3_f32 v2, v2, v143, v127
	v_max3_f32 v2, v2, v144, v128
	v_max3_f32 v2, v2, v145, v129
	v_mov_b32_e32 v4, v2
	s_nop 1
	v_permlane32_swap_b32_e32 v4, v2
	s_nop 0
	v_max_f32_e32 v2, v2, v4
	v_cndmask_b32_e64 v2, v186, v2, s[8:9]
	v_add_f32_e32 v4, 0x42317218, v216
	v_cmp_gt_f32_e32 vcc, v2, v4
	s_cbranch_vccz .LBB0_774
	s_nop 0
	v_cndmask_b32_e32 v4, v216, v2, vcc
	v_sub_f32_e32 v2, v216, v4
	v_mul_f32_e32 v2, 0x3e38aa3b, v2
	v_exp_f32_e32 v2, v2
	v_mov_b32_e32 v216, v4
	v_cndmask_b32_e32 v2, 1.0, v2, vcc
	v_mul_f32_e32 v214, v214, v2
	v_pk_mul_f32 v[80:81], v[80:81], v[2:3] op_sel_hi:[1,0]
	v_pk_mul_f32 v[78:79], v[78:79], v[2:3] op_sel_hi:[1,0]
	v_pk_mul_f32 v[76:77], v[76:77], v[2:3] op_sel_hi:[1,0]
	v_pk_mul_f32 v[74:75], v[74:75], v[2:3] op_sel_hi:[1,0]
	v_pk_mul_f32 v[72:73], v[72:73], v[2:3] op_sel_hi:[1,0]
	v_pk_mul_f32 v[70:71], v[70:71], v[2:3] op_sel_hi:[1,0]
	v_pk_mul_f32 v[68:69], v[68:69], v[2:3] op_sel_hi:[1,0]
	v_pk_mul_f32 v[66:67], v[66:67], v[2:3] op_sel_hi:[1,0]
	v_pk_mul_f32 v[64:65], v[64:65], v[2:3] op_sel_hi:[1,0]
	v_pk_mul_f32 v[62:63], v[62:63], v[2:3] op_sel_hi:[1,0]
	v_pk_mul_f32 v[60:61], v[60:61], v[2:3] op_sel_hi:[1,0]
	v_pk_mul_f32 v[58:59], v[58:59], v[2:3] op_sel_hi:[1,0]
	v_pk_mul_f32 v[56:57], v[56:57], v[2:3] op_sel_hi:[1,0]
	v_pk_mul_f32 v[54:55], v[54:55], v[2:3] op_sel_hi:[1,0]
	v_pk_mul_f32 v[52:53], v[52:53], v[2:3] op_sel_hi:[1,0]
	v_pk_mul_f32 v[50:51], v[50:51], v[2:3] op_sel_hi:[1,0]

; #define LAS __attribute__((address_space(3)))
; #define MFMA32(a, b, c) __builtin_amdgcn_mfma_f32_32x32x16_bf16((a), (b), (c), 0, 0, 0)
; DI float fexp2(float x) { return __builtin_amdgcn_exp2f(x); }
; DI s16x4 vtr(const LAS unsigned char* p) { return __builtin_bit_cast(s16x4, __builtin_amdgcn_ds_read_tr16_b64_v4i16((LAS v4i16_t*)p)); }
; DI void flash_pv(FState& st, f32x16& p0, f32x16& p1, bool rowon, const LAS unsigned char* vb, int lane) {
;     ...
;     const float cl = rowon ? SM_C : 0.0f;
;     const float bl = rowon ? ((st.m == NINF) ? 0.0f : -st.m * SM_C) : NINF;
;     float sum = 0.f;
; #pragma unroll
;     for (int r = 0; r < 16; ++r) { p0[r] = fexp2(__builtin_fmaf(p0[r], cl, bl)); p1[r] = fexp2(__builtin_fmaf(p1[r], cl, bl)); sum += p0[r] + p1[r]; }
;     st.l += sum;
;     const int h = lane >> 5;
;     const int vx = (((lane & 15) >> 3) & 1) * 64;
;     const LAS unsigned char* vp = vb + (4 * h + ((lane & 15) >> 2)) * 128 + ((lane >> 4) & 1) * 32 + (lane & 3) * 8;
; #pragma unroll
;     for (int sub = 0; sub < 2; ++sub)
; #pragma unroll
;         for (int s2 = 0; s2 < 2; ++s2) {
;             const bf16x8 pf = pack8h(sub ? p1 : p0, s2);
;             const LAS unsigned char* vq = vp + (32 * sub + 16 * s2) * 128;
;             { const s16x4 lo = vtr(vq + vx), hi = vtr(vq + 1024 + vx); const bf16x8 vf = {lo[0], lo[1], lo[2], lo[3], hi[0], hi[1], hi[2], hi[3]}; st.o0 = MFMA32(vf, pf, st.o0); }
;             { const s16x4 lo = vtr(vq + (64 - vx)), hi = vtr(vq + 1024 + (64 - vx)); const bf16x8 vf = {lo[0], lo[1], lo[2], lo[3], hi[0], hi[1], hi[2], hi[3]}; st.o1 = MFMA32(vf, pf, st.o1); }
;         }
.LBB0_778:
	s_or_b64 exec, exec, s[4:5]
	v_fma_f32 v2, v130, v5, v4
	v_exp_f32_e32 v12, v2
	v_fma_f32 v2, v114, v5, v4
	v_exp_f32_e32 v246, v2
	s_waitcnt lgkmcnt(3)
	v_mfma_f32_32x32x16_bf16 v[98:113], v[226:229], v[154:157], v[98:113]
	v_fma_f32 v2, v131, v5, v4
	v_exp_f32_e32 v6, v2
	v_fma_f32 v2, v115, v5, v4
	v_exp_f32_e32 v2, v2
	v_add_f32_e32 v7, v12, v246
	v_pk_add_f32 v[8:9], v[6:7], v[2:3]
	s_nop 0
	v_pk_add_f32 v[130:131], v[8:9], v[8:9] op_sel_hi:[0,1]
	v_fma_f32 v7, v132, v5, v4
	v_fma_f32 v8, v116, v5, v4
	s_waitcnt lgkmcnt(2)
	v_mfma_f32_32x32x16_bf16 v[82:97], v[230:233], v[154:157], v[82:97]
	v_exp_f32_e32 v7, v7
	v_exp_f32_e32 v247, v8
	v_fma_f32 v8, v133, v5, v4
	v_fma_f32 v9, v117, v5, v4
	v_exp_f32_e32 v8, v8
	v_exp_f32_e32 v130, v9
	v_add_f32_e32 v9, v7, v247
	v_cvt_pk_bf16_f32 v6, v12, v6
	v_cvt_pk_bf16_f32 v7, v7, v8
	v_pk_add_f32 v[10:11], v[8:9], v[130:131]
	s_waitcnt lgkmcnt(1)
	v_mfma_f32_32x32x16_bf16 v[98:113], v[234:237], v[158:161], v[98:113]
	v_fma_f32 v9, v134, v5, v4
	v_pk_add_f32 v[132:133], v[10:11], v[10:11] op_sel_hi:[0,1]
	v_fma_f32 v10, v118, v5, v4
	v_exp_f32_e32 v131, v10
	v_fma_f32 v10, v135, v5, v4
	v_exp_f32_e32 v9, v9
	v_exp_f32_e32 v14, v10
	v_fma_f32 v10, v119, v5, v4
	v_exp_f32_e32 v132, v10
	v_add_f32_e32 v15, v9, v131
	s_waitcnt lgkmcnt(0)
	v_mfma_f32_32x32x16_bf16 v[82:97], v[238:241], v[158:161], v[82:97]
	v_cvt_pk_bf16_f32 v8, v9, v14
	v_pk_add_f32 v[10:11], v[14:15], v[132:133]
	s_nop 0
	v_pk_add_f32 v[118:119], v[10:11], v[10:11] op_sel_hi:[0,1]
	v_fma_f32 v10, v136, v5, v4
	v_exp_f32_e32 v15, v10
	v_fma_f32 v10, v120, v5, v4
	v_exp_f32_e32 v133, v10
	v_fma_f32 v10, v137, v5, v4
	v_exp_f32_e32 v16, v10
	v_fma_f32 v10, v121, v5, v4
	v_exp_f32_e32 v118, v10
	v_add_f32_e32 v17, v15, v133
	v_cvt_pk_bf16_f32 v9, v15, v16
	v_pk_add_f32 v[10:11], v[16:17], v[118:119]
	s_nop 0
	v_pk_add_f32 v[120:121], v[10:11], v[10:11] op_sel_hi:[0,1]
	v_fma_f32 v10, v138, v5, v4
	v_exp_f32_e32 v119, v10
	v_fma_f32 v10, v122, v5, v4
	v_exp_f32_e32 v248, v10
	v_fma_f32 v10, v139, v5, v4
	v_exp_f32_e32 v122, v10
	v_fma_f32 v10, v123, v5, v4
	v_exp_f32_e32 v120, v10
	v_fma_f32 v10, v140, v5, v4
	v_exp_f32_e32 v139, v10
	v_fma_f32 v10, v124, v5, v4
	v_add_f32_e32 v123, v119, v248
	v_exp_f32_e32 v140, v10
	v_pk_add_f32 v[10:11], v[122:123], v[120:121]
	v_fma_f32 v123, v144, v5, v4
	v_pk_add_f32 v[134:135], v[10:11], v[10:11] op_sel_hi:[0,1]
	v_fma_f32 v10, v141, v5, v4
	v_exp_f32_e32 v136, v10
	v_fma_f32 v10, v125, v5, v4
	v_exp_f32_e32 v134, v10
	v_add_u32_e32 v10, s76, v211
	v_add3_u32 v17, v10, v203, v204
	v_add_u32_e32 v121, v17, v202
	ds_read_b64_tr_b16 v[10:11], v121 offset:8192
	ds_read_b64_tr_b16 v[12:13], v121 offset:9216
	v_add_u32_e32 v141, v17, v213
	ds_read_b64_tr_b16 v[14:15], v141 offset:8256
	ds_read_b64_tr_b16 v[16:17], v141 offset:9280
	ds_read_b64_tr_b16 v[114:115], v121 offset:10240
	ds_read_b64_tr_b16 v[116:117], v121 offset:11264
	s_waitcnt lgkmcnt(4)
	v_mfma_f32_32x32x16_bf16 v[66:81], v[10:13], v[6:9], v[66:81]
	v_fma_f32 v10, v142, v5, v4
	v_exp_f32_e32 v125, v10
	v_fma_f32 v10, v143, v5, v4
	v_exp_f32_e32 v124, v10
	v_exp_f32_e32 v142, v123
	v_add_f32_e32 v137, v139, v140
	ds_read_b64_tr_b16 v[10:11], v141 offset:10304
	ds_read_b64_tr_b16 v[12:13], v141 offset:11328
	s_waitcnt lgkmcnt(4)
	v_mfma_f32_32x32x16_bf16 v[50:65], v[14:17], v[6:9], v[50:65]
	v_fma_f32 v6, v145, v5, v4
	v_exp_f32_e32 v138, v6
	v_cvt_pk_bf16_f32 v6, v119, v122
	v_cvt_pk_bf16_f32 v7, v139, v136
	v_cvt_pk_bf16_f32 v8, v125, v124
	v_cvt_pk_bf16_f32 v9, v142, v138
	v_pk_add_f32 v[14:15], v[136:137], v[134:135]
	s_waitcnt lgkmcnt(2)
	v_mfma_f32_32x32x16_bf16 v[66:81], v[114:117], v[6:9], v[66:81]
	v_add_f32_e64 v122, v14, v14
	v_add_f32_e64 v123, v14, v15
	v_fma_f32 v14, v126, v5, v4
	v_exp_f32_e32 v126, v14
	ds_read_b64_tr_b16 v[14:15], v121 offset:12288
	ds_read_b64_tr_b16 v[16:17], v121 offset:13312
	v_fma_f32 v114, v127, v5, v4
	v_exp_f32_e32 v122, v114
	v_add_f32_e32 v125, v125, v126
	s_waitcnt lgkmcnt(2)
	v_mfma_f32_32x32x16_bf16 v[50:65], v[10:13], v[6:9], v[50:65]
	v_cvt_pk_bf16_f32 v6, v246, v2
	v_cvt_pk_bf16_f32 v7, v247, v130
	v_cvt_pk_bf16_f32 v8, v131, v132
	v_cvt_pk_bf16_f32 v9, v133, v118
	ds_read_b64_tr_b16 v[10:11], v121 offset:14336
	ds_read_b64_tr_b16 v[12:13], v121 offset:15360
	v_pk_add_f32 v[114:115], v[124:125], v[122:123]
	v_fma_f32 v2, v128, v5, v4
	s_waitcnt lgkmcnt(2)
	v_mfma_f32_32x32x16_bf16 v[66:81], v[14:17], v[6:9], v[66:81]
	ds_read_b64_tr_b16 v[14:15], v141 offset:12352
	ds_read_b64_tr_b16 v[16:17], v141 offset:13376
	v_add_f32_e64 v118, v114, v114
	v_add_f32_e64 v119, v114, v115
	v_fmac_f32_e32 v4, v129, v5
	ds_read_b64_tr_b16 v[114:115], v141 offset:14400
	ds_read_b64_tr_b16 v[116:117], v141 offset:15424
	v_exp_f32_e32 v2, v2
	v_exp_f32_e32 v118, v4
	v_cvt_pk_bf16_f32 v4, v248, v120
	s_waitcnt lgkmcnt(2)
	v_mfma_f32_32x32x16_bf16 v[50:65], v[14:17], v[6:9], v[50:65]
	v_cvt_pk_bf16_f32 v5, v140, v134
	v_cvt_pk_bf16_f32 v6, v126, v122
	v_cvt_pk_bf16_f32 v7, v2, v118
	v_add_f32_e32 v139, v142, v2
	v_add_f32_e64 v8, v138, v118
	v_add_f32_e64 v9, v139, v119
	v_add_f32_e32 v2, v8, v9
	v_mfma_f32_32x32x16_bf16 v[66:81], v[10:13], v[4:7], v[66:81]
	v_add_f32_e32 v214, v214, v2
	s_waitcnt lgkmcnt(0)
	v_mfma_f32_32x32x16_bf16 v[50:65], v[114:117], v[4:7], v[50:65]
	s_add_i32 s76, s74, 2
	s_cmp_ge_u32 s76, s51
	s_cbranch_scc0 .LBB0_781

.LBB0_785:
	s_add_i32 s10, s52, 3
	s_cmp_gt_u32 s76, s69
	s_cselect_b64 s[8:9], -1, 0
	s_and_b64 vcc, s[8:9], exec
	s_cselect_b32 s8, s10, s76
	v_lshl_or_b32 v2, s8, 6, v194
	s_mov_b64 s[10:11], -1
	s_cbranch_vccnz .LBB0_789
	v_lshrrev_b32_e32 v4, s76, v196
	v_and_b32_e32 v4, 1, v4
	v_cmp_eq_u32_e64 s[8:9], 1, v4
	s_cmp_lg_u32 s71, s74
	s_cbranch_scc1 .LBB0_788
	v_cmp_le_i32_e32 vcc, v2, v190
	v_or_b32_e32 v4, 32, v2
	s_nop 0
	v_cndmask_b32_e32 v98, v186, v98, vcc
	v_cmp_le_i32_e32 vcc, v4, v190
	v_or_b32_e32 v4, 33, v2
	s_nop 0
	v_cndmask_b32_e32 v82, v186, v82, vcc
	v_cmp_lt_i32_e32 vcc, v2, v190
	s_nop 1
	v_cndmask_b32_e32 v99, v186, v99, vcc
	v_cmp_le_i32_e32 vcc, v4, v190
	v_or_b32_e32 v4, 2, v2
	s_nop 0
	v_cndmask_b32_e32 v83, v186, v83, vcc
	v_cmp_le_i32_e32 vcc, v4, v190
	v_or_b32_e32 v4, 34, v2
	s_nop 0
	v_cndmask_b32_e32 v100, v186, v100, vcc
	v_cmp_le_i32_e32 vcc, v4, v190
	v_or_b32_e32 v4, 3, v2
	s_nop 0
	v_cndmask_b32_e32 v84, v186, v84, vcc
	v_cmp_le_i32_e32 vcc, v4, v190
	v_or_b32_e32 v4, 35, v2
	s_nop 0
	v_cndmask_b32_e32 v101, v186, v101, vcc
	v_cmp_le_i32_e32 vcc, v4, v190
	v_or_b32_e32 v4, 8, v2
	s_nop 0
	v_cndmask_b32_e32 v85, v186, v85, vcc
	v_cmp_le_i32_e32 vcc, v4, v190
	v_or_b32_e32 v4, 40, v2
	s_nop 0
	v_cndmask_b32_e32 v102, v186, v102, vcc
	v_cmp_le_i32_e32 vcc, v4, v190
	v_or_b32_e32 v4, 9, v2
	s_nop 0
	v_cndmask_b32_e32 v86, v186, v86, vcc
	v_cmp_le_i32_e32 vcc, v4, v190
	v_or_b32_e32 v4, 41, v2
	s_nop 0
	v_cndmask_b32_e32 v103, v186, v103, vcc
	v_cmp_le_i32_e32 vcc, v4, v190
	v_or_b32_e32 v4, 10, v2
	s_nop 0
	v_cndmask_b32_e32 v87, v186, v87, vcc
	v_cmp_le_i32_e32 vcc, v4, v190
	v_or_b32_e32 v4, 42, v2
	s_nop 0
	v_cndmask_b32_e32 v104, v186, v104, vcc
	v_cmp_le_i32_e32 vcc, v4, v190
	v_or_b32_e32 v4, 11, v2
	s_nop 0
	v_cndmask_b32_e32 v88, v186, v88, vcc
	v_cmp_le_i32_e32 vcc, v4, v190
	v_or_b32_e32 v4, 43, v2
	s_nop 0
	v_cndmask_b32_e32 v105, v186, v105, vcc
	v_cmp_le_i32_e32 vcc, v4, v190
	v_or_b32_e32 v4, 16, v2
	s_nop 0
	v_cndmask_b32_e32 v89, v186, v89, vcc
	v_cmp_le_i32_e32 vcc, v4, v190
	v_or_b32_e32 v4, 48, v2
	s_nop 0
	v_cndmask_b32_e32 v106, v186, v106, vcc
	v_cmp_le_i32_e32 vcc, v4, v190
	v_or_b32_e32 v4, 17, v2
	s_nop 0
	v_cndmask_b32_e32 v90, v186, v90, vcc
	v_cmp_le_i32_e32 vcc, v4, v190
	v_or_b32_e32 v4, 49, v2
	s_nop 0
	v_cndmask_b32_e32 v107, v186, v107, vcc
	v_cmp_le_i32_e32 vcc, v4, v190
	v_or_b32_e32 v4, 18, v2
	s_nop 0
	v_cndmask_b32_e32 v91, v186, v91, vcc
	v_cmp_le_i32_e32 vcc, v4, v190
	v_or_b32_e32 v4, 50, v2
	s_nop 0
	v_cndmask_b32_e32 v108, v186, v108, vcc
	v_cmp_le_i32_e32 vcc, v4, v190
	v_or_b32_e32 v4, 19, v2
	s_nop 0
	v_cndmask_b32_e32 v92, v186, v92, vcc
	v_cmp_le_i32_e32 vcc, v4, v190
	v_or_b32_e32 v4, 51, v2
	s_nop 0
	v_cndmask_b32_e32 v109, v186, v109, vcc
	v_cmp_le_i32_e32 vcc, v4, v190
	v_or_b32_e32 v4, 24, v2
	s_nop 0
	v_cndmask_b32_e32 v93, v186, v93, vcc
	v_cmp_le_i32_e32 vcc, v4, v190
	v_or_b32_e32 v4, 56, v2
	s_nop 0
	v_cndmask_b32_e32 v110, v186, v110, vcc
	v_cmp_le_i32_e32 vcc, v4, v190
	v_or_b32_e32 v4, 25, v2
	s_nop 0
	v_cndmask_b32_e32 v94, v186, v94, vcc
	v_cmp_le_i32_e32 vcc, v4, v190
	v_or_b32_e32 v4, 57, v2
	s_nop 0
	v_cndmask_b32_e32 v111, v186, v111, vcc
	v_cmp_le_i32_e32 vcc, v4, v190
	v_or_b32_e32 v4, 26, v2
	s_nop 0
	v_cndmask_b32_e32 v95, v186, v95, vcc
	v_cmp_le_i32_e32 vcc, v4, v190
	v_or_b32_e32 v4, 58, v2
	s_nop 0
	v_cndmask_b32_e32 v112, v186, v112, vcc
	v_cmp_le_i32_e32 vcc, v4, v190
	v_or_b32_e32 v4, 27, v2
	s_nop 0
	v_cndmask_b32_e32 v96, v186, v96, vcc
	v_cmp_le_i32_e32 vcc, v4, v190
	v_or_b32_e32 v4, 59, v2
	s_nop 0
	v_cndmask_b32_e32 v113, v186, v113, vcc
	v_cmp_le_i32_e32 vcc, v4, v190
	s_nop 1
	v_cndmask_b32_e32 v97, v186, v97, vcc

.LBB0_789:
	s_andn2_b64 vcc, exec, s[10:11]
	s_cbranch_vccnz .LBB0_793
	s_cmp_eq_u32 s75, 7
	s_cselect_b64 s[8:9], -1, 0
	s_or_b64 s[4:5], s[4:5], s[8:9]
	s_andn2_b64 vcc, exec, s[4:5]
	s_cbranch_vccnz .LBB0_792
	v_cmp_le_i32_e32 vcc, v2, v190
	v_cmp_gt_i32_e64 s[4:5], v2, v210
	s_and_b64 vcc, vcc, s[4:5]
	v_or_b32_e32 v4, 32, v2
	v_cndmask_b32_e32 v98, v186, v98, vcc
	v_cmp_le_i32_e32 vcc, v4, v190
	v_cmp_gt_i32_e64 s[4:5], v4, v210
	s_and_b64 vcc, vcc, s[4:5]
	v_cndmask_b32_e32 v82, v186, v82, vcc
	v_cmp_lt_i32_e32 vcc, v2, v190
	v_cmp_ge_i32_e64 s[4:5], v2, v210
	s_and_b64 vcc, vcc, s[4:5]
	v_or_b32_e32 v4, 33, v2
	v_cndmask_b32_e32 v99, v186, v99, vcc
	v_cmp_le_i32_e32 vcc, v4, v190
	v_cmp_gt_i32_e64 s[4:5], v4, v210
	s_and_b64 vcc, vcc, s[4:5]
	v_or_b32_e32 v4, 2, v2
	v_cndmask_b32_e32 v83, v186, v83, vcc
	v_cmp_le_i32_e32 vcc, v4, v190
	v_cmp_gt_i32_e64 s[4:5], v4, v210
	s_and_b64 vcc, vcc, s[4:5]
	v_or_b32_e32 v4, 34, v2
	v_cndmask_b32_e32 v100, v186, v100, vcc
	v_cmp_le_i32_e32 vcc, v4, v190
	v_cmp_gt_i32_e64 s[4:5], v4, v210
	s_and_b64 vcc, vcc, s[4:5]
	v_or_b32_e32 v4, 3, v2
	v_cndmask_b32_e32 v84, v186, v84, vcc
	v_cmp_le_i32_e32 vcc, v4, v190
	v_cmp_gt_i32_e64 s[4:5], v4, v210
	s_and_b64 vcc, vcc, s[4:5]
	v_or_b32_e32 v4, 35, v2
	v_cndmask_b32_e32 v101, v186, v101, vcc
	v_cmp_le_i32_e32 vcc, v4, v190
	v_cmp_gt_i32_e64 s[4:5], v4, v210
	s_and_b64 vcc, vcc, s[4:5]
	v_or_b32_e32 v4, 8, v2
	v_cndmask_b32_e32 v85, v186, v85, vcc
	v_cmp_le_i32_e32 vcc, v4, v190
	v_cmp_gt_i32_e64 s[4:5], v4, v210
	s_and_b64 vcc, vcc, s[4:5]
	v_or_b32_e32 v4, 40, v2
	v_cndmask_b32_e32 v102, v186, v102, vcc
	v_cmp_le_i32_e32 vcc, v4, v190
	v_cmp_gt_i32_e64 s[4:5], v4, v210
	s_and_b64 vcc, vcc, s[4:5]
	v_or_b32_e32 v4, 9, v2
	v_cndmask_b32_e32 v86, v186, v86, vcc
	v_cmp_le_i32_e32 vcc, v4, v190
	v_cmp_gt_i32_e64 s[4:5], v4, v210
	s_and_b64 vcc, vcc, s[4:5]
	v_or_b32_e32 v4, 41, v2
	v_cndmask_b32_e32 v103, v186, v103, vcc
	v_cmp_le_i32_e32 vcc, v4, v190
	v_cmp_gt_i32_e64 s[4:5], v4, v210
	s_and_b64 vcc, vcc, s[4:5]
	v_or_b32_e32 v4, 10, v2
	v_cndmask_b32_e32 v87, v186, v87, vcc
	v_cmp_le_i32_e32 vcc, v4, v190
	v_cmp_gt_i32_e64 s[4:5], v4, v210
	s_and_b64 vcc, vcc, s[4:5]
	v_or_b32_e32 v4, 42, v2
	v_cndmask_b32_e32 v104, v186, v104, vcc
	v_cmp_le_i32_e32 vcc, v4, v190
	v_cmp_gt_i32_e64 s[4:5], v4, v210
	s_and_b64 vcc, vcc, s[4:5]
	v_or_b32_e32 v4, 11, v2
	v_cndmask_b32_e32 v88, v186, v88, vcc
	v_cmp_le_i32_e32 vcc, v4, v190
	v_cmp_gt_i32_e64 s[4:5], v4, v210
	s_and_b64 vcc, vcc, s[4:5]
	v_or_b32_e32 v4, 43, v2
	v_cndmask_b32_e32 v105, v186, v105, vcc
	v_cmp_le_i32_e32 vcc, v4, v190
	v_cmp_gt_i32_e64 s[4:5], v4, v210
	s_and_b64 vcc, vcc, s[4:5]
	v_or_b32_e32 v4, 16, v2
	v_cndmask_b32_e32 v89, v186, v89, vcc
	v_cmp_le_i32_e32 vcc, v4, v190
	v_cmp_gt_i32_e64 s[4:5], v4, v210
	s_and_b64 vcc, vcc, s[4:5]
	v_or_b32_e32 v4, 48, v2
	v_cndmask_b32_e32 v106, v186, v106, vcc
	v_cmp_le_i32_e32 vcc, v4, v190
	v_cmp_gt_i32_e64 s[4:5], v4, v210
	s_and_b64 vcc, vcc, s[4:5]
	v_or_b32_e32 v4, 17, v2
	v_cndmask_b32_e32 v90, v186, v90, vcc
	v_cmp_le_i32_e32 vcc, v4, v190
	v_cmp_gt_i32_e64 s[4:5], v4, v210
	s_and_b64 vcc, vcc, s[4:5]
	v_or_b32_e32 v4, 49, v2
	v_cndmask_b32_e32 v107, v186, v107, vcc
	v_cmp_le_i32_e32 vcc, v4, v190
	v_cmp_gt_i32_e64 s[4:5], v4, v210
	s_and_b64 vcc, vcc, s[4:5]
	v_or_b32_e32 v4, 18, v2
	v_cndmask_b32_e32 v91, v186, v91, vcc
	v_cmp_le_i32_e32 vcc, v4, v190
	v_cmp_gt_i32_e64 s[4:5], v4, v210
	s_and_b64 vcc, vcc, s[4:5]
	v_or_b32_e32 v4, 50, v2
	v_cndmask_b32_e32 v108, v186, v108, vcc
	v_cmp_le_i32_e32 vcc, v4, v190
	v_cmp_gt_i32_e64 s[4:5], v4, v210
	s_and_b64 vcc, vcc, s[4:5]
	v_or_b32_e32 v4, 19, v2
	v_cndmask_b32_e32 v92, v186, v92, vcc
	v_cmp_le_i32_e32 vcc, v4, v190
	v_cmp_gt_i32_e64 s[4:5], v4, v210
	s_and_b64 vcc, vcc, s[4:5]
	v_or_b32_e32 v4, 51, v2
	v_cndmask_b32_e32 v109, v186, v109, vcc
	v_cmp_le_i32_e32 vcc, v4, v190
	v_cmp_gt_i32_e64 s[4:5], v4, v210
	s_and_b64 vcc, vcc, s[4:5]
	v_or_b32_e32 v4, 24, v2
	v_cndmask_b32_e32 v93, v186, v93, vcc
	v_cmp_le_i32_e32 vcc, v4, v190
	v_cmp_gt_i32_e64 s[4:5], v4, v210
	s_and_b64 vcc, vcc, s[4:5]
	v_or_b32_e32 v4, 56, v2
	v_cndmask_b32_e32 v110, v186, v110, vcc
	v_cmp_le_i32_e32 vcc, v4, v190
	v_cmp_gt_i32_e64 s[4:5], v4, v210
	s_and_b64 vcc, vcc, s[4:5]
	v_or_b32_e32 v4, 25, v2
	v_cndmask_b32_e32 v94, v186, v94, vcc
	v_cmp_le_i32_e32 vcc, v4, v190
	v_cmp_gt_i32_e64 s[4:5], v4, v210
	s_and_b64 vcc, vcc, s[4:5]
	v_or_b32_e32 v4, 57, v2
	v_cndmask_b32_e32 v111, v186, v111, vcc
	v_cmp_le_i32_e32 vcc, v4, v190
	v_cmp_gt_i32_e64 s[4:5], v4, v210
	s_and_b64 vcc, vcc, s[4:5]
	v_or_b32_e32 v4, 26, v2
	v_cndmask_b32_e32 v95, v186, v95, vcc
	v_cmp_le_i32_e32 vcc, v4, v190
	v_cmp_gt_i32_e64 s[4:5], v4, v210
	s_and_b64 vcc, vcc, s[4:5]
	v_or_b32_e32 v4, 58, v2
	v_cndmask_b32_e32 v112, v186, v112, vcc
	v_cmp_le_i32_e32 vcc, v4, v190
	v_cmp_gt_i32_e64 s[4:5], v4, v210
	s_and_b64 vcc, vcc, s[4:5]
	v_or_b32_e32 v4, 27, v2
	v_cndmask_b32_e32 v96, v186, v96, vcc
	v_cmp_le_i32_e32 vcc, v4, v190
	v_cmp_gt_i32_e64 s[4:5], v4, v210
	s_and_b64 vcc, vcc, s[4:5]
	v_or_b32_e32 v2, 59, v2
	v_cndmask_b32_e32 v113, v186, v113, vcc
	v_cmp_le_i32_e32 vcc, v2, v190
	v_cmp_gt_i32_e64 s[4:5], v2, v210
	s_and_b64 vcc, vcc, s[4:5]
	v_cndmask_b32_e32 v97, v186, v97, vcc
.LBB0_792:
	s_nop 1
	s_nop 0
	s_mov_b64 s[8:9], -1

.LBB0_800:
	s_mov_b32 s74, s73
	s_branch .Lnq_741
.Lnq_741:
	s_mov_b32 s76, 0
	s_add_i32 s73, s74, 3
	s_cmp_ge_u32 s73, s51
	s_cselect_b64 s[6:7], -1, 0
	s_waitcnt vmcnt(1)
	ds_write_b128 v205, v[170:173] offset:16384
	s_waitcnt vmcnt(0)
	ds_write_b128 v212, v[174:177] offset:24576
	s_waitcnt lgkmcnt(0)
	s_barrier
	s_cmp_lg_u32 s74, 0
	s_cbranch_scc1 .Lnq_not3
	s_and_b64 vcc, exec, s[6:7]
	s_cbranch_vccnz .Lnq_not3
	s_cmp_gt_u32 s73, s69
	s_cselect_b64 s[4:5], -1, 0
	s_add_i32 s8, s52, 2
	s_and_b64 s[4:5], s[4:5], exec
	s_cselect_b32 s8, s8, s73
	s_cselect_b32 s16, 0x1000, s65
	s_cselect_b32 s4, s64, 0x500
	s_lshl_b32 s8, s8, 6
	s_mov_b32 s5, s17
	v_mad_i64_i32 v[4:5], s[8:9], s8, v199, v[192:193]
	v_lshl_add_u64 v[6:7], v[4:5], 0, s[4:5]
	v_lshl_add_u64 v[4:5], v[4:5], 0, s[16:17]
	global_load_dwordx4 v[162:165], v[6:7], off
	global_load_dwordx4 v[166:169], v[4:5], off

.Lnq_745:
	s_add_i32 s10, s52, 5
	s_cmp_gt_u32 s74, s69
	s_cselect_b64 s[8:9], -1, 0
	s_and_b64 vcc, s[8:9], exec
	s_cselect_b32 s8, s10, s74
	v_lshl_or_b32 v2, s8, 6, v194
	s_mov_b64 s[10:11], -1
	s_cbranch_vccnz .Lnq_749
	v_lshrrev_b32_e32 v4, s74, v196
	v_and_b32_e32 v4, 1, v4
	v_cmp_eq_u32_e64 s[8:9], 1, v4
	s_cmp_lg_u32 s69, s74
	s_cbranch_scc1 .Lnq_748
	v_cmp_le_i32_e32 vcc, v2, v190
	v_or_b32_e32 v4, 32, v2
	s_nop 0
	v_cndmask_b32_e32 v130, v186, v130, vcc
	v_cmp_le_i32_e32 vcc, v4, v190
	v_or_b32_e32 v4, 33, v2
	s_nop 0
	v_cndmask_b32_e32 v114, v186, v114, vcc
	v_cmp_lt_i32_e32 vcc, v2, v190
	s_nop 1
	v_cndmask_b32_e32 v131, v186, v131, vcc
	v_cmp_le_i32_e32 vcc, v4, v190
	v_or_b32_e32 v4, 2, v2
	s_nop 0
	v_cndmask_b32_e32 v115, v186, v115, vcc
	v_cmp_le_i32_e32 vcc, v4, v190
	v_or_b32_e32 v4, 34, v2
	s_nop 0
	v_cndmask_b32_e32 v132, v186, v132, vcc
	v_cmp_le_i32_e32 vcc, v4, v190
	v_or_b32_e32 v4, 3, v2
	s_nop 0
	v_cndmask_b32_e32 v116, v186, v116, vcc
	v_cmp_le_i32_e32 vcc, v4, v190
	v_or_b32_e32 v4, 35, v2
	s_nop 0
	v_cndmask_b32_e32 v133, v186, v133, vcc
	v_cmp_le_i32_e32 vcc, v4, v190
	v_or_b32_e32 v4, 8, v2
	s_nop 0
	v_cndmask_b32_e32 v117, v186, v117, vcc
	v_cmp_le_i32_e32 vcc, v4, v190
	v_or_b32_e32 v4, 40, v2
	s_nop 0
	v_cndmask_b32_e32 v134, v186, v134, vcc
	v_cmp_le_i32_e32 vcc, v4, v190
	v_or_b32_e32 v4, 9, v2
	s_nop 0
	v_cndmask_b32_e32 v118, v186, v118, vcc
	v_cmp_le_i32_e32 vcc, v4, v190
	v_or_b32_e32 v4, 41, v2
	s_nop 0
	v_cndmask_b32_e32 v135, v186, v135, vcc
	v_cmp_le_i32_e32 vcc, v4, v190
	v_or_b32_e32 v4, 10, v2
	s_nop 0
	v_cndmask_b32_e32 v119, v186, v119, vcc
	v_cmp_le_i32_e32 vcc, v4, v190
	v_or_b32_e32 v4, 42, v2
	s_nop 0
	v_cndmask_b32_e32 v136, v186, v136, vcc
	v_cmp_le_i32_e32 vcc, v4, v190
	v_or_b32_e32 v4, 11, v2
	s_nop 0
	v_cndmask_b32_e32 v120, v186, v120, vcc
	v_cmp_le_i32_e32 vcc, v4, v190
	v_or_b32_e32 v4, 43, v2
	s_nop 0
	v_cndmask_b32_e32 v137, v186, v137, vcc
	v_cmp_le_i32_e32 vcc, v4, v190
	v_or_b32_e32 v4, 16, v2
	s_nop 0
	v_cndmask_b32_e32 v121, v186, v121, vcc
	v_cmp_le_i32_e32 vcc, v4, v190
	v_or_b32_e32 v4, 48, v2
	s_nop 0
	v_cndmask_b32_e32 v138, v186, v138, vcc
	v_cmp_le_i32_e32 vcc, v4, v190
	v_or_b32_e32 v4, 17, v2
	s_nop 0
	v_cndmask_b32_e32 v122, v186, v122, vcc
	v_cmp_le_i32_e32 vcc, v4, v190
	v_or_b32_e32 v4, 49, v2
	s_nop 0
	v_cndmask_b32_e32 v139, v186, v139, vcc
	v_cmp_le_i32_e32 vcc, v4, v190
	v_or_b32_e32 v4, 18, v2
	s_nop 0
	v_cndmask_b32_e32 v123, v186, v123, vcc
	v_cmp_le_i32_e32 vcc, v4, v190
	v_or_b32_e32 v4, 50, v2
	s_nop 0
	v_cndmask_b32_e32 v140, v186, v140, vcc
	v_cmp_le_i32_e32 vcc, v4, v190
	v_or_b32_e32 v4, 19, v2
	s_nop 0
	v_cndmask_b32_e32 v124, v186, v124, vcc
	v_cmp_le_i32_e32 vcc, v4, v190
	v_or_b32_e32 v4, 51, v2
	s_nop 0
	v_cndmask_b32_e32 v141, v186, v141, vcc
	v_cmp_le_i32_e32 vcc, v4, v190
	v_or_b32_e32 v4, 24, v2
	s_nop 0
	v_cndmask_b32_e32 v125, v186, v125, vcc
	v_cmp_le_i32_e32 vcc, v4, v190
	v_or_b32_e32 v4, 56, v2
	s_nop 0
	v_cndmask_b32_e32 v142, v186, v142, vcc
	v_cmp_le_i32_e32 vcc, v4, v190
	v_or_b32_e32 v4, 25, v2
	s_nop 0
	v_cndmask_b32_e32 v126, v186, v126, vcc
	v_cmp_le_i32_e32 vcc, v4, v190
	v_or_b32_e32 v4, 57, v2
	s_nop 0
	v_cndmask_b32_e32 v143, v186, v143, vcc
	v_cmp_le_i32_e32 vcc, v4, v190
	v_or_b32_e32 v4, 26, v2
	s_nop 0
	v_cndmask_b32_e32 v127, v186, v127, vcc
	v_cmp_le_i32_e32 vcc, v4, v190
	v_or_b32_e32 v4, 58, v2
	s_nop 0
	v_cndmask_b32_e32 v144, v186, v144, vcc
	v_cmp_le_i32_e32 vcc, v4, v190
	v_or_b32_e32 v4, 27, v2
	s_nop 0
	v_cndmask_b32_e32 v128, v186, v128, vcc
	v_cmp_le_i32_e32 vcc, v4, v190
	v_or_b32_e32 v4, 59, v2
	s_nop 0
	v_cndmask_b32_e32 v145, v186, v145, vcc
	v_cmp_le_i32_e32 vcc, v4, v190
	s_nop 1
	v_cndmask_b32_e32 v129, v186, v129, vcc

; #define LAS __attribute__((address_space(3)))
; #define MFMA32(a, b, c) __builtin_amdgcn_mfma_f32_32x32x16_bf16((a), (b), (c), 0, 0, 0)
; DI float fexp2(float x) { return __builtin_amdgcn_exp2f(x); }
; DI float half_max(float v) { return fmaxf(v, __shfl_xor(v, 32)); }
; DI void flash_qk(const LAS unsigned char* kb, const bf16x8 (&qf)[4], f32x16& p0, f32x16& p1, int r32, int h) {
;     p0 = f16zero(); p1 = f16zero();
;     const int sw = (r32 >> 1) & 7;
; #pragma unroll
;     for (int s = 0; s < 4; ++s) {
;         const int off = r32 * 128 + (((2 * s + h) ^ sw) << 4);
;         const bf16x8 a0 = *(const LAS bf16x8*)(kb + off), a1 = *(const LAS bf16x8*)(kb + off + 4096);
;         p0 = MFMA32(a0, qf[s], p0); p1 = MFMA32(a1, qf[s], p1);
;     }
; DI void flash_pv(FState& st, f32x16& p0, f32x16& p1, bool rowon, const LAS unsigned char* vb, int lane) {
;     float mx = fmaxf(p0[0], p1[0]);
; #pragma unroll
;     for (int r = 1; r < 16; ++r) asm("v_max3_f32 %0, %1, %2, %3" : "=v"(mx) : "v"(mx), "v"(p0[r]), "v"(p1[r]));
;     mx = half_max(mx);
;     mx = rowon ? mx : NINF;
;     const bool upd = mx > st.m + THR_RAW;
;     if (__any(upd)) {
;         const float mn = upd ? mx : st.m;
;         const float alpha = upd ? fexp2((st.m - mn) * SM_C) : 1.0f;
;         st.m = mn; st.l *= alpha;
; #pragma unroll
;         for (int r = 0; r < 16; ++r) { st.o0[r] *= alpha; st.o1[r] *= alpha; }
;     }
.Lnq_753:
	v_max_f32_e32 v2, v114, v114
	v_max_f32_e32 v4, v130, v130
	v_max_f32_e32 v2, v4, v2
	s_waitcnt lgkmcnt(3)
	v_mfma_f32_32x32x16_bf16 v[98:113], v[226:229], v[146:149], 0
	v_max3_f32 v2, v2, v131, v115
	v_and_b32_e32 v5, 64, v198
	v_max3_f32 v2, v2, v132, v116
	v_xor_b32_e32 v4, 32, v198
	s_waitcnt lgkmcnt(2)
	v_mfma_f32_32x32x16_bf16 v[82:97], v[230:233], v[146:149], 0
	ds_read_b128 v[226:229], v223 offset:16384
	ds_read_b128 v[230:233], v223 offset:20480
	v_max3_f32 v2, v2, v133, v117
	v_add_u32_e32 v5, 64, v5
	v_max3_f32 v2, v2, v134, v118
	v_cmp_lt_i32_e32 vcc, v4, v5
	s_waitcnt lgkmcnt(3)
	v_mfma_f32_32x32x16_bf16 v[98:113], v[234:237], v[150:153], v[98:113]
	v_max3_f32 v2, v2, v135, v119
	v_max3_f32 v2, v2, v136, v120
	v_max3_f32 v2, v2, v137, v121
	v_cndmask_b32_e32 v4, v198, v4, vcc
	s_waitcnt lgkmcnt(2)
	v_mfma_f32_32x32x16_bf16 v[82:97], v[238:241], v[150:153], v[82:97]
	ds_read_b128 v[234:237], v224 offset:16384
	ds_read_b128 v[238:241], v224 offset:20480
	v_max3_f32 v2, v2, v138, v122
	v_lshlrev_b32_e32 v215, 2, v4
	v_max3_f32 v2, v2, v139, v123
	v_max3_f32 v2, v2, v140, v124
	v_max3_f32 v2, v2, v141, v125
	v_max3_f32 v2, v2, v142, v126
	v_max3_f32 v2, v2, v143, v127
	v_max3_f32 v2, v2, v144, v128
	v_max3_f32 v2, v2, v145, v129
	v_mov_b32_e32 v4, v2
	s_nop 1
	v_permlane32_swap_b32_e32 v4, v2
	s_nop 0
	v_max_f32_e32 v2, v2, v4
	v_cndmask_b32_e64 v2, v186, v2, s[8:9]
	v_add_f32_e32 v4, 0x42317218, v216
	v_cmp_gt_f32_e32 vcc, v2, v4
	s_cbranch_vccz .Lnq_755
	s_nop 0
	v_cndmask_b32_e32 v4, v216, v2, vcc
	v_sub_f32_e32 v2, v216, v4
	v_mul_f32_e32 v2, 0x3e38aa3b, v2
	v_exp_f32_e32 v2, v2
	v_mov_b32_e32 v216, v4
	v_cndmask_b32_e32 v2, 1.0, v2, vcc
	v_mul_f32_e32 v214, v214, v2
	v_pk_mul_f32 v[80:81], v[80:81], v[2:3] op_sel_hi:[1,0]
	v_pk_mul_f32 v[78:79], v[78:79], v[2:3] op_sel_hi:[1,0]
	v_pk_mul_f32 v[76:77], v[76:77], v[2:3] op_sel_hi:[1,0]
	v_pk_mul_f32 v[74:75], v[74:75], v[2:3] op_sel_hi:[1,0]
	v_pk_mul_f32 v[72:73], v[72:73], v[2:3] op_sel_hi:[1,0]
	v_pk_mul_f32 v[70:71], v[70:71], v[2:3] op_sel_hi:[1,0]
	v_pk_mul_f32 v[68:69], v[68:69], v[2:3] op_sel_hi:[1,0]
	v_pk_mul_f32 v[66:67], v[66:67], v[2:3] op_sel_hi:[1,0]
	v_pk_mul_f32 v[64:65], v[64:65], v[2:3] op_sel_hi:[1,0]
	v_pk_mul_f32 v[62:63], v[62:63], v[2:3] op_sel_hi:[1,0]
	v_pk_mul_f32 v[60:61], v[60:61], v[2:3] op_sel_hi:[1,0]
	v_pk_mul_f32 v[58:59], v[58:59], v[2:3] op_sel_hi:[1,0]
	v_pk_mul_f32 v[56:57], v[56:57], v[2:3] op_sel_hi:[1,0]
	v_pk_mul_f32 v[54:55], v[54:55], v[2:3] op_sel_hi:[1,0]
	v_pk_mul_f32 v[52:53], v[52:53], v[2:3] op_sel_hi:[1,0]
	v_pk_mul_f32 v[50:51], v[50:51], v[2:3] op_sel_hi:[1,0]

; #define LAS __attribute__((address_space(3)))
; #define MFMA32(a, b, c) __builtin_amdgcn_mfma_f32_32x32x16_bf16((a), (b), (c), 0, 0, 0)
; DI float fexp2(float x) { return __builtin_amdgcn_exp2f(x); }
; DI s16x4 vtr(const LAS unsigned char* p) { return __builtin_bit_cast(s16x4, __builtin_amdgcn_ds_read_tr16_b64_v4i16((LAS v4i16_t*)p)); }
; DI void flash_pv(FState& st, f32x16& p0, f32x16& p1, bool rowon, const LAS unsigned char* vb, int lane) {
;     ...
;     const float cl = rowon ? SM_C : 0.0f;
;     const float bl = rowon ? ((st.m == NINF) ? 0.0f : -st.m * SM_C) : NINF;
;     float sum = 0.f;
; #pragma unroll
;     for (int r = 0; r < 16; ++r) { p0[r] = fexp2(__builtin_fmaf(p0[r], cl, bl)); p1[r] = fexp2(__builtin_fmaf(p1[r], cl, bl)); sum += p0[r] + p1[r]; }
;     st.l += sum;
;     const int h = lane >> 5;
;     const int vx = (((lane & 15) >> 3) & 1) * 64;
;     const LAS unsigned char* vp = vb + (4 * h + ((lane & 15) >> 2)) * 128 + ((lane >> 4) & 1) * 32 + (lane & 3) * 8;
; #pragma unroll
;     for (int sub = 0; sub < 2; ++sub)
; #pragma unroll
;         for (int s2 = 0; s2 < 2; ++s2) {
;             const bf16x8 pf = pack8h(sub ? p1 : p0, s2);
;             const LAS unsigned char* vq = vp + (32 * sub + 16 * s2) * 128;
;             { const s16x4 lo = vtr(vq + vx), hi = vtr(vq + 1024 + vx); const bf16x8 vf = {lo[0], lo[1], lo[2], lo[3], hi[0], hi[1], hi[2], hi[3]}; st.o0 = MFMA32(vf, pf, st.o0); }
;             { const s16x4 lo = vtr(vq + (64 - vx)), hi = vtr(vq + 1024 + (64 - vx)); const bf16x8 vf = {lo[0], lo[1], lo[2], lo[3], hi[0], hi[1], hi[2], hi[3]}; st.o1 = MFMA32(vf, pf, st.o1); }
;         }
.Lnq_759:
	s_or_b64 exec, exec, s[4:5]
	v_fma_f32 v2, v130, v5, v4
	v_exp_f32_e32 v12, v2
	v_fma_f32 v2, v114, v5, v4
	v_exp_f32_e32 v246, v2
	s_waitcnt lgkmcnt(3)
	v_mfma_f32_32x32x16_bf16 v[98:113], v[226:229], v[154:157], v[98:113]
	v_fma_f32 v2, v131, v5, v4
	v_exp_f32_e32 v6, v2
	v_fma_f32 v2, v115, v5, v4
	v_exp_f32_e32 v2, v2
	v_add_f32_e32 v7, v12, v246
	s_add_i32 s77, s74, 1
	s_cmp_ge_u32 s77, s51
	v_pk_add_f32 v[8:9], v[6:7], v[2:3]
	v_fma_f32 v7, v132, v5, v4
	v_pk_add_f32 v[130:131], v[8:9], v[8:9] op_sel_hi:[0,1]
	s_waitcnt lgkmcnt(2)
	v_mfma_f32_32x32x16_bf16 v[82:97], v[230:233], v[154:157], v[82:97]
	v_fma_f32 v8, v116, v5, v4
	v_exp_f32_e32 v7, v7
	v_exp_f32_e32 v247, v8
	v_fma_f32 v8, v133, v5, v4
	v_fma_f32 v9, v117, v5, v4
	v_exp_f32_e32 v8, v8
	v_exp_f32_e32 v130, v9
	v_add_f32_e32 v9, v7, v247
	v_cvt_pk_bf16_f32 v6, v12, v6
	v_cvt_pk_bf16_f32 v7, v7, v8
	s_waitcnt lgkmcnt(1)
	v_mfma_f32_32x32x16_bf16 v[98:113], v[234:237], v[158:161], v[98:113]
	v_pk_add_f32 v[10:11], v[8:9], v[130:131]
	v_fma_f32 v9, v134, v5, v4
	v_pk_add_f32 v[132:133], v[10:11], v[10:11] op_sel_hi:[0,1]
	v_fma_f32 v10, v118, v5, v4
	v_exp_f32_e32 v131, v10
	v_fma_f32 v10, v135, v5, v4
	v_exp_f32_e32 v9, v9
	v_exp_f32_e32 v14, v10
	v_fma_f32 v10, v119, v5, v4
	v_exp_f32_e32 v132, v10
	s_waitcnt lgkmcnt(0)
	v_mfma_f32_32x32x16_bf16 v[82:97], v[238:241], v[158:161], v[82:97]
	v_add_f32_e32 v15, v9, v131
	v_cvt_pk_bf16_f32 v8, v9, v14
	v_pk_add_f32 v[10:11], v[14:15], v[132:133]
	s_nop 0
	v_pk_add_f32 v[118:119], v[10:11], v[10:11] op_sel_hi:[0,1]
	v_fma_f32 v10, v136, v5, v4
	v_exp_f32_e32 v15, v10
	v_fma_f32 v10, v120, v5, v4
	v_exp_f32_e32 v133, v10
	v_fma_f32 v10, v137, v5, v4
	v_exp_f32_e32 v16, v10
	v_fma_f32 v10, v121, v5, v4
	v_exp_f32_e32 v118, v10
	v_add_f32_e32 v17, v15, v133
	v_cvt_pk_bf16_f32 v9, v15, v16
	v_pk_add_f32 v[10:11], v[16:17], v[118:119]
	s_nop 0
	v_pk_add_f32 v[120:121], v[10:11], v[10:11] op_sel_hi:[0,1]
	v_fma_f32 v10, v138, v5, v4
	v_exp_f32_e32 v119, v10
	v_fma_f32 v10, v122, v5, v4
	v_exp_f32_e32 v248, v10
	v_fma_f32 v10, v139, v5, v4
	v_exp_f32_e32 v122, v10
	v_fma_f32 v10, v123, v5, v4
	v_exp_f32_e32 v120, v10
	v_fma_f32 v10, v140, v5, v4
	v_exp_f32_e32 v139, v10
	v_fma_f32 v10, v124, v5, v4
	v_add_f32_e32 v123, v119, v248
	v_exp_f32_e32 v140, v10
	v_pk_add_f32 v[10:11], v[122:123], v[120:121]
	v_fma_f32 v123, v144, v5, v4
	v_pk_add_f32 v[134:135], v[10:11], v[10:11] op_sel_hi:[0,1]
	v_fma_f32 v10, v141, v5, v4
	v_exp_f32_e32 v136, v10
	v_fma_f32 v10, v125, v5, v4
	v_exp_f32_e32 v134, v10
	v_add_u32_e32 v10, s76, v211
	v_add3_u32 v17, v10, v203, v204
	v_add_u32_e32 v218, v17, v202
	ds_read_b64_tr_b16 v[10:11], v218 offset:8192
	ds_read_b64_tr_b16 v[12:13], v218 offset:9216
	v_add_u32_e32 v217, v17, v213
	ds_read_b64_tr_b16 v[14:15], v217 offset:8256
	ds_read_b64_tr_b16 v[16:17], v217 offset:9280
	ds_read_b64_tr_b16 v[114:115], v218 offset:10240
	ds_read_b64_tr_b16 v[116:117], v218 offset:11264
	s_waitcnt lgkmcnt(4)
	v_mfma_f32_32x32x16_bf16 v[66:81], v[10:13], v[6:9], v[66:81]
	v_fma_f32 v10, v142, v5, v4
	v_exp_f32_e32 v121, v10
	v_fma_f32 v10, v143, v5, v4
	v_exp_f32_e32 v124, v10
	v_exp_f32_e32 v141, v123
	v_add_f32_e32 v137, v139, v140
	ds_read_b64_tr_b16 v[10:11], v217 offset:10304
	ds_read_b64_tr_b16 v[12:13], v217 offset:11328
	s_waitcnt lgkmcnt(4)
	v_mfma_f32_32x32x16_bf16 v[50:65], v[14:17], v[6:9], v[50:65]
	v_fma_f32 v6, v145, v5, v4
	v_exp_f32_e32 v138, v6
	v_cvt_pk_bf16_f32 v6, v119, v122
	v_cvt_pk_bf16_f32 v7, v139, v136
	v_cvt_pk_bf16_f32 v8, v121, v124
	v_cvt_pk_bf16_f32 v9, v141, v138
	v_pk_add_f32 v[14:15], v[136:137], v[134:135]
	s_waitcnt lgkmcnt(2)
	v_mfma_f32_32x32x16_bf16 v[66:81], v[114:117], v[6:9], v[66:81]
	v_add_f32_e64 v122, v14, v14
	v_add_f32_e64 v123, v14, v15
	v_fma_f32 v14, v126, v5, v4
	v_exp_f32_e32 v126, v14
	ds_read_b64_tr_b16 v[14:15], v218 offset:12288
	ds_read_b64_tr_b16 v[16:17], v218 offset:13312
	v_fma_f32 v114, v127, v5, v4
	v_exp_f32_e32 v122, v114
	v_add_f32_e32 v125, v121, v126
	s_waitcnt lgkmcnt(2)
	v_mfma_f32_32x32x16_bf16 v[50:65], v[10:13], v[6:9], v[50:65]
	v_cvt_pk_bf16_f32 v6, v246, v2
	v_cvt_pk_bf16_f32 v7, v247, v130
	v_cvt_pk_bf16_f32 v8, v131, v132
	v_cvt_pk_bf16_f32 v9, v133, v118
	ds_read_b64_tr_b16 v[10:11], v218 offset:14336
	ds_read_b64_tr_b16 v[12:13], v218 offset:15360
	v_pk_add_f32 v[114:115], v[124:125], v[122:123]
	v_fma_f32 v2, v128, v5, v4
	s_waitcnt lgkmcnt(2)
	v_mfma_f32_32x32x16_bf16 v[66:81], v[14:17], v[6:9], v[66:81]
	ds_read_b64_tr_b16 v[14:15], v217 offset:12352
	ds_read_b64_tr_b16 v[16:17], v217 offset:13376
	v_add_f32_e64 v118, v114, v114
	v_add_f32_e64 v119, v114, v115
	v_fmac_f32_e32 v4, v129, v5
	ds_read_b64_tr_b16 v[114:115], v217 offset:14400
	ds_read_b64_tr_b16 v[116:117], v217 offset:15424
	v_exp_f32_e32 v2, v2
	v_exp_f32_e32 v118, v4
	v_cvt_pk_bf16_f32 v4, v248, v120
	s_waitcnt lgkmcnt(2)
	v_mfma_f32_32x32x16_bf16 v[50:65], v[14:17], v[6:9], v[50:65]
	v_cvt_pk_bf16_f32 v5, v140, v134
	v_cvt_pk_bf16_f32 v6, v126, v122
	v_cvt_pk_bf16_f32 v7, v2, v118
	v_add_f32_e32 v139, v141, v2
	v_add_f32_e64 v8, v138, v118
	v_add_f32_e64 v9, v139, v119
	v_add_f32_e32 v2, v8, v9
	v_mfma_f32_32x32x16_bf16 v[66:81], v[10:13], v[4:7], v[66:81]
	v_add_f32_e32 v214, v214, v2
	s_waitcnt lgkmcnt(0)
	v_mfma_f32_32x32x16_bf16 v[50:65], v[114:117], v[4:7], v[50:65]
	s_cbranch_scc1 .Lnq_780
	s_movk_i32 s76, 0x4000
	s_add_i32 s4, s74, 5
	s_cmp_ge_u32 s4, s51
	s_waitcnt vmcnt(1)
	ds_write_b128 v205, v[182:185] offset:32768
	s_waitcnt vmcnt(0)
	ds_write_b128 v212, v[178:181] offset:40960
	s_waitcnt lgkmcnt(0)
	s_barrier
	s_cbranch_scc1 .Lnq_762
	s_cmp_gt_u32 s4, s69
	s_cselect_b64 s[8:9], -1, 0
	s_mov_b32 s5, s52
	s_and_b64 s[8:9], s[8:9], exec
	s_cselect_b32 s4, s5, s4
	s_cselect_b32 s16, 0x1000, s65
	s_cselect_b32 s8, s64, 0x500
	s_lshl_b32 s4, s4, 6
	s_mov_b32 s9, s17
	v_mad_i64_i32 v[4:5], s[4:5], s4, v199, v[192:193]
	v_lshl_add_u64 v[6:7], v[4:5], 0, s[8:9]
	v_lshl_add_u64 v[4:5], v[4:5], 0, s[16:17]
	global_load_dwordx4 v[182:185], v[6:7], off
	global_load_dwordx4 v[178:181], v[4:5], off

.Lnq_764:
	s_add_i32 s8, s52, 4
	s_cmp_lt_u32 s74, s69
	s_cselect_b32 s8, s77, s8
	s_cmp_ge_u32 s74, s69
	s_mov_b64 s[10:11], -1
	v_lshl_or_b32 v2, s8, 6, v194
	s_mov_b64 s[8:9], -1
	s_cbranch_scc0 .Lnq_768
	s_cmp_eq_u32 s75, 8
	s_cselect_b64 s[10:11], -1, 0
	s_or_b64 s[4:5], s[4:5], s[10:11]
	s_andn2_b64 vcc, exec, s[4:5]
	s_cbranch_vccnz .Lnq_767
	v_cmp_le_i32_e32 vcc, v2, v190
	v_cmp_gt_i32_e64 s[4:5], v2, v210
	s_and_b64 vcc, vcc, s[4:5]
	v_or_b32_e32 v4, 32, v2
	v_cndmask_b32_e32 v98, v186, v98, vcc
	v_cmp_le_i32_e32 vcc, v4, v190
	v_cmp_gt_i32_e64 s[4:5], v4, v210
	s_and_b64 vcc, vcc, s[4:5]
	v_cndmask_b32_e32 v82, v186, v82, vcc
	v_cmp_lt_i32_e32 vcc, v2, v190
	v_cmp_ge_i32_e64 s[4:5], v2, v210
	s_and_b64 vcc, vcc, s[4:5]
	v_or_b32_e32 v4, 33, v2
	v_cndmask_b32_e32 v99, v186, v99, vcc
	v_cmp_le_i32_e32 vcc, v4, v190
	v_cmp_gt_i32_e64 s[4:5], v4, v210
	s_and_b64 vcc, vcc, s[4:5]
	v_or_b32_e32 v4, 2, v2
	v_cndmask_b32_e32 v83, v186, v83, vcc
	v_cmp_le_i32_e32 vcc, v4, v190
	v_cmp_gt_i32_e64 s[4:5], v4, v210
	s_and_b64 vcc, vcc, s[4:5]
	v_or_b32_e32 v4, 34, v2
	v_cndmask_b32_e32 v100, v186, v100, vcc
	v_cmp_le_i32_e32 vcc, v4, v190
	v_cmp_gt_i32_e64 s[4:5], v4, v210
	s_and_b64 vcc, vcc, s[4:5]
	v_or_b32_e32 v4, 3, v2
	v_cndmask_b32_e32 v84, v186, v84, vcc
	v_cmp_le_i32_e32 vcc, v4, v190
	v_cmp_gt_i32_e64 s[4:5], v4, v210
	s_and_b64 vcc, vcc, s[4:5]
	v_or_b32_e32 v4, 35, v2
	v_cndmask_b32_e32 v101, v186, v101, vcc
	v_cmp_le_i32_e32 vcc, v4, v190
	v_cmp_gt_i32_e64 s[4:5], v4, v210
	s_and_b64 vcc, vcc, s[4:5]
	v_or_b32_e32 v4, 8, v2
	v_cndmask_b32_e32 v85, v186, v85, vcc
	v_cmp_le_i32_e32 vcc, v4, v190
	v_cmp_gt_i32_e64 s[4:5], v4, v210
	s_and_b64 vcc, vcc, s[4:5]
	v_or_b32_e32 v4, 40, v2
	v_cndmask_b32_e32 v102, v186, v102, vcc
	v_cmp_le_i32_e32 vcc, v4, v190
	v_cmp_gt_i32_e64 s[4:5], v4, v210
	s_and_b64 vcc, vcc, s[4:5]
	v_or_b32_e32 v4, 9, v2
	v_cndmask_b32_e32 v86, v186, v86, vcc
	v_cmp_le_i32_e32 vcc, v4, v190
	v_cmp_gt_i32_e64 s[4:5], v4, v210
	s_and_b64 vcc, vcc, s[4:5]
	v_or_b32_e32 v4, 41, v2
	v_cndmask_b32_e32 v103, v186, v103, vcc
	v_cmp_le_i32_e32 vcc, v4, v190
	v_cmp_gt_i32_e64 s[4:5], v4, v210
	s_and_b64 vcc, vcc, s[4:5]
	v_or_b32_e32 v4, 10, v2
	v_cndmask_b32_e32 v87, v186, v87, vcc
	v_cmp_le_i32_e32 vcc, v4, v190
	v_cmp_gt_i32_e64 s[4:5], v4, v210
	s_and_b64 vcc, vcc, s[4:5]
	v_or_b32_e32 v4, 42, v2
	v_cndmask_b32_e32 v104, v186, v104, vcc
	v_cmp_le_i32_e32 vcc, v4, v190
	v_cmp_gt_i32_e64 s[4:5], v4, v210
	s_and_b64 vcc, vcc, s[4:5]
	v_or_b32_e32 v4, 11, v2
	v_cndmask_b32_e32 v88, v186, v88, vcc
	v_cmp_le_i32_e32 vcc, v4, v190
	v_cmp_gt_i32_e64 s[4:5], v4, v210
	s_and_b64 vcc, vcc, s[4:5]
	v_or_b32_e32 v4, 43, v2
	v_cndmask_b32_e32 v105, v186, v105, vcc
	v_cmp_le_i32_e32 vcc, v4, v190
	v_cmp_gt_i32_e64 s[4:5], v4, v210
	s_and_b64 vcc, vcc, s[4:5]
	v_or_b32_e32 v4, 16, v2
	v_cndmask_b32_e32 v89, v186, v89, vcc
	v_cmp_le_i32_e32 vcc, v4, v190
	v_cmp_gt_i32_e64 s[4:5], v4, v210
	s_and_b64 vcc, vcc, s[4:5]
	v_or_b32_e32 v4, 48, v2
	v_cndmask_b32_e32 v106, v186, v106, vcc
	v_cmp_le_i32_e32 vcc, v4, v190
	v_cmp_gt_i32_e64 s[4:5], v4, v210
	s_and_b64 vcc, vcc, s[4:5]
	v_or_b32_e32 v4, 17, v2
	v_cndmask_b32_e32 v90, v186, v90, vcc
	v_cmp_le_i32_e32 vcc, v4, v190
	v_cmp_gt_i32_e64 s[4:5], v4, v210
	s_and_b64 vcc, vcc, s[4:5]
	v_or_b32_e32 v4, 49, v2
	v_cndmask_b32_e32 v107, v186, v107, vcc
	v_cmp_le_i32_e32 vcc, v4, v190
	v_cmp_gt_i32_e64 s[4:5], v4, v210
	s_and_b64 vcc, vcc, s[4:5]
	v_or_b32_e32 v4, 18, v2
	v_cndmask_b32_e32 v91, v186, v91, vcc
	v_cmp_le_i32_e32 vcc, v4, v190
	v_cmp_gt_i32_e64 s[4:5], v4, v210
	s_and_b64 vcc, vcc, s[4:5]
	v_or_b32_e32 v4, 50, v2
	v_cndmask_b32_e32 v108, v186, v108, vcc
	v_cmp_le_i32_e32 vcc, v4, v190
	v_cmp_gt_i32_e64 s[4:5], v4, v210
	s_and_b64 vcc, vcc, s[4:5]
	v_or_b32_e32 v4, 19, v2
	v_cndmask_b32_e32 v92, v186, v92, vcc
	v_cmp_le_i32_e32 vcc, v4, v190
	v_cmp_gt_i32_e64 s[4:5], v4, v210
	s_and_b64 vcc, vcc, s[4:5]
	v_or_b32_e32 v4, 51, v2
	v_cndmask_b32_e32 v109, v186, v109, vcc
	v_cmp_le_i32_e32 vcc, v4, v190
	v_cmp_gt_i32_e64 s[4:5], v4, v210
	s_and_b64 vcc, vcc, s[4:5]
	v_or_b32_e32 v4, 24, v2
	v_cndmask_b32_e32 v93, v186, v93, vcc
	v_cmp_le_i32_e32 vcc, v4, v190
	v_cmp_gt_i32_e64 s[4:5], v4, v210
	s_and_b64 vcc, vcc, s[4:5]
	v_or_b32_e32 v4, 56, v2
	v_cndmask_b32_e32 v110, v186, v110, vcc
	v_cmp_le_i32_e32 vcc, v4, v190
	v_cmp_gt_i32_e64 s[4:5], v4, v210
	s_and_b64 vcc, vcc, s[4:5]
	v_or_b32_e32 v4, 25, v2
	v_cndmask_b32_e32 v94, v186, v94, vcc
	v_cmp_le_i32_e32 vcc, v4, v190
	v_cmp_gt_i32_e64 s[4:5], v4, v210
	s_and_b64 vcc, vcc, s[4:5]
	v_or_b32_e32 v4, 57, v2
	v_cndmask_b32_e32 v111, v186, v111, vcc
	v_cmp_le_i32_e32 vcc, v4, v190
	v_cmp_gt_i32_e64 s[4:5], v4, v210
	s_and_b64 vcc, vcc, s[4:5]
	v_or_b32_e32 v4, 26, v2
	v_cndmask_b32_e32 v95, v186, v95, vcc
	v_cmp_le_i32_e32 vcc, v4, v190
	v_cmp_gt_i32_e64 s[4:5], v4, v210
	s_and_b64 vcc, vcc, s[4:5]
	v_or_b32_e32 v4, 58, v2
	v_cndmask_b32_e32 v112, v186, v112, vcc
	v_cmp_le_i32_e32 vcc, v4, v190
	v_cmp_gt_i32_e64 s[4:5], v4, v210
	s_and_b64 vcc, vcc, s[4:5]
	v_or_b32_e32 v4, 27, v2
	v_cndmask_b32_e32 v96, v186, v96, vcc
	v_cmp_le_i32_e32 vcc, v4, v190
	v_cmp_gt_i32_e64 s[4:5], v4, v210
	s_and_b64 vcc, vcc, s[4:5]
	v_or_b32_e32 v4, 59, v2
	v_cndmask_b32_e32 v113, v186, v113, vcc
	v_cmp_le_i32_e32 vcc, v4, v190
	v_cmp_gt_i32_e64 s[4:5], v4, v210
	s_and_b64 vcc, vcc, s[4:5]
	v_cndmask_b32_e32 v97, v186, v97, vcc

.Lnq_768:
	s_andn2_b64 vcc, exec, s[10:11]
	s_cbranch_vccnz .Lnq_772
	v_lshrrev_b32_e32 v4, s77, v196
	v_and_b32_e32 v4, 1, v4
	s_cmp_lg_u32 s72, s74
	v_cmp_eq_u32_e64 s[8:9], 1, v4
	s_cbranch_scc1 .Lnq_771
	v_cmp_le_i32_e32 vcc, v2, v190
	v_or_b32_e32 v4, 32, v2
	s_nop 0
	v_cndmask_b32_e32 v98, v186, v98, vcc
	v_cmp_le_i32_e32 vcc, v4, v190
	v_or_b32_e32 v4, 33, v2
	s_nop 0
	v_cndmask_b32_e32 v82, v186, v82, vcc
	v_cmp_lt_i32_e32 vcc, v2, v190
	s_nop 1
	v_cndmask_b32_e32 v99, v186, v99, vcc
	v_cmp_le_i32_e32 vcc, v4, v190
	v_or_b32_e32 v4, 2, v2
	s_nop 0
	v_cndmask_b32_e32 v83, v186, v83, vcc
	v_cmp_le_i32_e32 vcc, v4, v190
	v_or_b32_e32 v4, 34, v2
	s_nop 0
	v_cndmask_b32_e32 v100, v186, v100, vcc
	v_cmp_le_i32_e32 vcc, v4, v190
	v_or_b32_e32 v4, 3, v2
	s_nop 0
	v_cndmask_b32_e32 v84, v186, v84, vcc
	v_cmp_le_i32_e32 vcc, v4, v190
	v_or_b32_e32 v4, 35, v2
	s_nop 0
	v_cndmask_b32_e32 v101, v186, v101, vcc
	v_cmp_le_i32_e32 vcc, v4, v190
	v_or_b32_e32 v4, 8, v2
	s_nop 0
	v_cndmask_b32_e32 v85, v186, v85, vcc
	v_cmp_le_i32_e32 vcc, v4, v190
	v_or_b32_e32 v4, 40, v2
	s_nop 0
	v_cndmask_b32_e32 v102, v186, v102, vcc
	v_cmp_le_i32_e32 vcc, v4, v190
	v_or_b32_e32 v4, 9, v2
	s_nop 0
	v_cndmask_b32_e32 v86, v186, v86, vcc
	v_cmp_le_i32_e32 vcc, v4, v190
	v_or_b32_e32 v4, 41, v2
	s_nop 0
	v_cndmask_b32_e32 v103, v186, v103, vcc
	v_cmp_le_i32_e32 vcc, v4, v190
	v_or_b32_e32 v4, 10, v2
	s_nop 0
	v_cndmask_b32_e32 v87, v186, v87, vcc
	v_cmp_le_i32_e32 vcc, v4, v190
	v_or_b32_e32 v4, 42, v2
	s_nop 0
	v_cndmask_b32_e32 v104, v186, v104, vcc
	v_cmp_le_i32_e32 vcc, v4, v190
	v_or_b32_e32 v4, 11, v2
	s_nop 0
	v_cndmask_b32_e32 v88, v186, v88, vcc
	v_cmp_le_i32_e32 vcc, v4, v190
	v_or_b32_e32 v4, 43, v2
	s_nop 0
	v_cndmask_b32_e32 v105, v186, v105, vcc
	v_cmp_le_i32_e32 vcc, v4, v190
	v_or_b32_e32 v4, 16, v2
	s_nop 0
	v_cndmask_b32_e32 v89, v186, v89, vcc
	v_cmp_le_i32_e32 vcc, v4, v190
	v_or_b32_e32 v4, 48, v2
	s_nop 0
	v_cndmask_b32_e32 v106, v186, v106, vcc
	v_cmp_le_i32_e32 vcc, v4, v190
	v_or_b32_e32 v4, 17, v2
	s_nop 0
	v_cndmask_b32_e32 v90, v186, v90, vcc
	v_cmp_le_i32_e32 vcc, v4, v190
	v_or_b32_e32 v4, 49, v2
	s_nop 0
	v_cndmask_b32_e32 v107, v186, v107, vcc
	v_cmp_le_i32_e32 vcc, v4, v190
	v_or_b32_e32 v4, 18, v2
	s_nop 0
	v_cndmask_b32_e32 v91, v186, v91, vcc
	v_cmp_le_i32_e32 vcc, v4, v190
	v_or_b32_e32 v4, 50, v2
	s_nop 0
	v_cndmask_b32_e32 v108, v186, v108, vcc
	v_cmp_le_i32_e32 vcc, v4, v190
	v_or_b32_e32 v4, 19, v2
	s_nop 0
	v_cndmask_b32_e32 v92, v186, v92, vcc
	v_cmp_le_i32_e32 vcc, v4, v190
	v_or_b32_e32 v4, 51, v2
	s_nop 0
	v_cndmask_b32_e32 v109, v186, v109, vcc
	v_cmp_le_i32_e32 vcc, v4, v190
	v_or_b32_e32 v4, 24, v2
	s_nop 0
	v_cndmask_b32_e32 v93, v186, v93, vcc
	v_cmp_le_i32_e32 vcc, v4, v190
	v_or_b32_e32 v4, 56, v2
	s_nop 0
	v_cndmask_b32_e32 v110, v186, v110, vcc
	v_cmp_le_i32_e32 vcc, v4, v190
	v_or_b32_e32 v4, 25, v2
	s_nop 0
	v_cndmask_b32_e32 v94, v186, v94, vcc
	v_cmp_le_i32_e32 vcc, v4, v190
	v_or_b32_e32 v4, 57, v2
	s_nop 0
	v_cndmask_b32_e32 v111, v186, v111, vcc
	v_cmp_le_i32_e32 vcc, v4, v190
	v_or_b32_e32 v4, 26, v2
	s_nop 0
	v_cndmask_b32_e32 v95, v186, v95, vcc
	v_cmp_le_i32_e32 vcc, v4, v190
	v_or_b32_e32 v4, 58, v2
	s_nop 0
	v_cndmask_b32_e32 v112, v186, v112, vcc
	v_cmp_le_i32_e32 vcc, v4, v190
	v_or_b32_e32 v4, 27, v2
	v_or_b32_e32 v2, 59, v2
	v_cndmask_b32_e32 v96, v186, v96, vcc
	v_cmp_le_i32_e32 vcc, v4, v190
	s_nop 1
	v_cndmask_b32_e32 v113, v186, v113, vcc
	v_cmp_le_i32_e32 vcc, v2, v190
	s_nop 1
	v_cndmask_b32_e32 v97, v186, v97, vcc

.Lnq_785:
	s_add_i32 s10, s52, 3
	s_cmp_gt_u32 s76, s69
	s_cselect_b64 s[8:9], -1, 0
	s_and_b64 vcc, s[8:9], exec
	s_cselect_b32 s8, s10, s76
	v_lshl_or_b32 v2, s8, 6, v194
	s_mov_b64 s[10:11], -1
	s_cbranch_vccnz .Lnq_789
	v_lshrrev_b32_e32 v4, s76, v196
	v_and_b32_e32 v4, 1, v4
	v_cmp_eq_u32_e64 s[8:9], 1, v4
	s_cmp_lg_u32 s71, s74
	s_cbranch_scc1 .Lnq_788
	v_cmp_le_i32_e32 vcc, v2, v190
	v_or_b32_e32 v4, 32, v2
	s_nop 0
	v_cndmask_b32_e32 v130, v186, v130, vcc
	v_cmp_le_i32_e32 vcc, v4, v190
	v_or_b32_e32 v4, 33, v2
	s_nop 0
	v_cndmask_b32_e32 v114, v186, v114, vcc
	v_cmp_lt_i32_e32 vcc, v2, v190
	s_nop 1
	v_cndmask_b32_e32 v131, v186, v131, vcc
	v_cmp_le_i32_e32 vcc, v4, v190
	v_or_b32_e32 v4, 2, v2
	s_nop 0
	v_cndmask_b32_e32 v115, v186, v115, vcc
	v_cmp_le_i32_e32 vcc, v4, v190
	v_or_b32_e32 v4, 34, v2
	s_nop 0
	v_cndmask_b32_e32 v132, v186, v132, vcc
	v_cmp_le_i32_e32 vcc, v4, v190
	v_or_b32_e32 v4, 3, v2
	s_nop 0
	v_cndmask_b32_e32 v116, v186, v116, vcc
	v_cmp_le_i32_e32 vcc, v4, v190
	v_or_b32_e32 v4, 35, v2
	s_nop 0
	v_cndmask_b32_e32 v133, v186, v133, vcc
	v_cmp_le_i32_e32 vcc, v4, v190
	v_or_b32_e32 v4, 8, v2
	s_nop 0
	v_cndmask_b32_e32 v117, v186, v117, vcc
	v_cmp_le_i32_e32 vcc, v4, v190
	v_or_b32_e32 v4, 40, v2
	s_nop 0
	v_cndmask_b32_e32 v134, v186, v134, vcc
	v_cmp_le_i32_e32 vcc, v4, v190
	v_or_b32_e32 v4, 9, v2
	s_nop 0
	v_cndmask_b32_e32 v118, v186, v118, vcc
	v_cmp_le_i32_e32 vcc, v4, v190
	v_or_b32_e32 v4, 41, v2
	s_nop 0
	v_cndmask_b32_e32 v135, v186, v135, vcc
	v_cmp_le_i32_e32 vcc, v4, v190
	v_or_b32_e32 v4, 10, v2
	s_nop 0
	v_cndmask_b32_e32 v119, v186, v119, vcc
	v_cmp_le_i32_e32 vcc, v4, v190
	v_or_b32_e32 v4, 42, v2
	s_nop 0
	v_cndmask_b32_e32 v136, v186, v136, vcc
	v_cmp_le_i32_e32 vcc, v4, v190
	v_or_b32_e32 v4, 11, v2
	s_nop 0
	v_cndmask_b32_e32 v120, v186, v120, vcc
	v_cmp_le_i32_e32 vcc, v4, v190
	v_or_b32_e32 v4, 43, v2
	s_nop 0
	v_cndmask_b32_e32 v137, v186, v137, vcc
	v_cmp_le_i32_e32 vcc, v4, v190
	v_or_b32_e32 v4, 16, v2
	s_nop 0
	v_cndmask_b32_e32 v121, v186, v121, vcc
	v_cmp_le_i32_e32 vcc, v4, v190
	v_or_b32_e32 v4, 48, v2
	s_nop 0
	v_cndmask_b32_e32 v138, v186, v138, vcc
	v_cmp_le_i32_e32 vcc, v4, v190
	v_or_b32_e32 v4, 17, v2
	s_nop 0
	v_cndmask_b32_e32 v122, v186, v122, vcc
	v_cmp_le_i32_e32 vcc, v4, v190
	v_or_b32_e32 v4, 49, v2
	s_nop 0
	v_cndmask_b32_e32 v139, v186, v139, vcc
	v_cmp_le_i32_e32 vcc, v4, v190
	v_or_b32_e32 v4, 18, v2
	s_nop 0
	v_cndmask_b32_e32 v123, v186, v123, vcc
	v_cmp_le_i32_e32 vcc, v4, v190
	v_or_b32_e32 v4, 50, v2
	s_nop 0
	v_cndmask_b32_e32 v140, v186, v140, vcc
	v_cmp_le_i32_e32 vcc, v4, v190
	v_or_b32_e32 v4, 19, v2
	s_nop 0
	v_cndmask_b32_e32 v124, v186, v124, vcc
	v_cmp_le_i32_e32 vcc, v4, v190
	v_or_b32_e32 v4, 51, v2
	s_nop 0
	v_cndmask_b32_e32 v141, v186, v141, vcc
	v_cmp_le_i32_e32 vcc, v4, v190
	v_or_b32_e32 v4, 24, v2
	s_nop 0
	v_cndmask_b32_e32 v125, v186, v125, vcc
	v_cmp_le_i32_e32 vcc, v4, v190
	v_or_b32_e32 v4, 56, v2
	s_nop 0
	v_cndmask_b32_e32 v142, v186, v142, vcc
	v_cmp_le_i32_e32 vcc, v4, v190
	v_or_b32_e32 v4, 25, v2
	s_nop 0
	v_cndmask_b32_e32 v126, v186, v126, vcc
	v_cmp_le_i32_e32 vcc, v4, v190
	v_or_b32_e32 v4, 57, v2
	s_nop 0
	v_cndmask_b32_e32 v143, v186, v143, vcc
	v_cmp_le_i32_e32 vcc, v4, v190
	v_or_b32_e32 v4, 26, v2
	s_nop 0
	v_cndmask_b32_e32 v127, v186, v127, vcc
	v_cmp_le_i32_e32 vcc, v4, v190
	v_or_b32_e32 v4, 58, v2
	s_nop 0
	v_cndmask_b32_e32 v144, v186, v144, vcc
	v_cmp_le_i32_e32 vcc, v4, v190
	v_or_b32_e32 v4, 27, v2
	s_nop 0
	v_cndmask_b32_e32 v128, v186, v128, vcc
	v_cmp_le_i32_e32 vcc, v4, v190
	v_or_b32_e32 v4, 59, v2
	s_nop 0
	v_cndmask_b32_e32 v145, v186, v145, vcc
	v_cmp_le_i32_e32 vcc, v4, v190
	s_nop 1
	v_cndmask_b32_e32 v129, v186, v129, vcc

; #define LAS __attribute__((address_space(3)))
; #define MFMA32(a, b, c) __builtin_amdgcn_mfma_f32_32x32x16_bf16((a), (b), (c), 0, 0, 0)
; DI float fexp2(float x) { return __builtin_amdgcn_exp2f(x); }
; DI float half_max(float v) { return fmaxf(v, __shfl_xor(v, 32)); }
; DI void flash_qk(const LAS unsigned char* kb, const bf16x8 (&qf)[4], f32x16& p0, f32x16& p1, int r32, int h) {
;     p0 = f16zero(); p1 = f16zero();
;     const int sw = (r32 >> 1) & 7;
; #pragma unroll
;     for (int s = 0; s < 4; ++s) {
;         const int off = r32 * 128 + (((2 * s + h) ^ sw) << 4);
;         const bf16x8 a0 = *(const LAS bf16x8*)(kb + off), a1 = *(const LAS bf16x8*)(kb + off + 4096);
;         p0 = MFMA32(a0, qf[s], p0); p1 = MFMA32(a1, qf[s], p1);
;     }
; DI void flash_pv(FState& st, f32x16& p0, f32x16& p1, bool rowon, const LAS unsigned char* vb, int lane) {
;     float mx = fmaxf(p0[0], p1[0]);
; #pragma unroll
;     for (int r = 1; r < 16; ++r) asm("v_max3_f32 %0, %1, %2, %3" : "=v"(mx) : "v"(mx), "v"(p0[r]), "v"(p1[r]));
;     mx = half_max(mx);
;     mx = rowon ? mx : NINF;
;     const bool upd = mx > st.m + THR_RAW;
;     if (__any(upd)) {
;         const float mn = upd ? mx : st.m;
;         const float alpha = upd ? fexp2((st.m - mn) * SM_C) : 1.0f;
;         st.m = mn; st.l *= alpha;
; #pragma unroll
;         for (int r = 0; r < 16; ++r) { st.o0[r] *= alpha; st.o1[r] *= alpha; }
;     }
.Lnq_793:
	v_max_f32_e32 v2, v114, v114
	v_max_f32_e32 v4, v130, v130
	v_max_f32_e32 v2, v4, v2
	s_waitcnt lgkmcnt(3)
	v_mfma_f32_32x32x16_bf16 v[98:113], v[226:229], v[146:149], 0
	v_max3_f32 v2, v2, v131, v115
	v_max3_f32 v2, v2, v132, v116
	v_max3_f32 v2, v2, v133, v117
	v_max3_f32 v2, v2, v134, v118
	s_waitcnt lgkmcnt(2)
	v_mfma_f32_32x32x16_bf16 v[82:97], v[230:233], v[146:149], 0
	ds_read_b128 v[226:229], v223
	ds_read_b128 v[230:233], v223 offset:4096
	v_max3_f32 v2, v2, v135, v119
	v_max3_f32 v2, v2, v136, v120
	v_max3_f32 v2, v2, v137, v121
	v_max3_f32 v2, v2, v138, v122
	s_waitcnt lgkmcnt(3)
	v_mfma_f32_32x32x16_bf16 v[98:113], v[234:237], v[150:153], v[98:113]
	v_max3_f32 v2, v2, v139, v123
	v_max3_f32 v2, v2, v140, v124
	v_max3_f32 v2, v2, v141, v125
	v_max3_f32 v2, v2, v142, v126
	s_waitcnt lgkmcnt(2)
	v_mfma_f32_32x32x16_bf16 v[82:97], v[238:241], v[150:153], v[82:97]
	ds_read_b128 v[234:237], v224
	ds_read_b128 v[238:241], v224 offset:4096
	v_max3_f32 v2, v2, v143, v127
	v_max3_f32 v2, v2, v144, v128
	v_max3_f32 v2, v2, v145, v129
	v_mov_b32_e32 v4, v2
	s_nop 1
	v_permlane32_swap_b32_e32 v4, v2
	s_nop 0
	v_max_f32_e32 v2, v2, v4
	v_cndmask_b32_e64 v2, v186, v2, s[8:9]
	v_add_f32_e32 v4, 0x42317218, v216
	v_cmp_gt_f32_e32 vcc, v2, v4
	s_cbranch_vccz .Lnq_795
	s_nop 0
	v_cndmask_b32_e32 v4, v216, v2, vcc
	v_sub_f32_e32 v2, v216, v4
	v_mul_f32_e32 v2, 0x3e38aa3b, v2
	v_exp_f32_e32 v2, v2
	v_mov_b32_e32 v216, v4
	v_cndmask_b32_e32 v2, 1.0, v2, vcc
	v_mul_f32_e32 v214, v214, v2
	v_pk_mul_f32 v[80:81], v[80:81], v[2:3] op_sel_hi:[1,0]
	v_pk_mul_f32 v[78:79], v[78:79], v[2:3] op_sel_hi:[1,0]
	v_pk_mul_f32 v[76:77], v[76:77], v[2:3] op_sel_hi:[1,0]
	v_pk_mul_f32 v[74:75], v[74:75], v[2:3] op_sel_hi:[1,0]
	v_pk_mul_f32 v[72:73], v[72:73], v[2:3] op_sel_hi:[1,0]
	v_pk_mul_f32 v[70:71], v[70:71], v[2:3] op_sel_hi:[1,0]
	v_pk_mul_f32 v[68:69], v[68:69], v[2:3] op_sel_hi:[1,0]
	v_pk_mul_f32 v[66:67], v[66:67], v[2:3] op_sel_hi:[1,0]
	v_pk_mul_f32 v[64:65], v[64:65], v[2:3] op_sel_hi:[1,0]
	v_pk_mul_f32 v[62:63], v[62:63], v[2:3] op_sel_hi:[1,0]
	v_pk_mul_f32 v[60:61], v[60:61], v[2:3] op_sel_hi:[1,0]
	v_pk_mul_f32 v[58:59], v[58:59], v[2:3] op_sel_hi:[1,0]
	v_pk_mul_f32 v[56:57], v[56:57], v[2:3] op_sel_hi:[1,0]
	v_pk_mul_f32 v[54:55], v[54:55], v[2:3] op_sel_hi:[1,0]
	v_pk_mul_f32 v[52:53], v[52:53], v[2:3] op_sel_hi:[1,0]
	v_pk_mul_f32 v[50:51], v[50:51], v[2:3] op_sel_hi:[1,0]

; #define LAS __attribute__((address_space(3)))
; #define MFMA32(a, b, c) __builtin_amdgcn_mfma_f32_32x32x16_bf16((a), (b), (c), 0, 0, 0)
; DI float fexp2(float x) { return __builtin_amdgcn_exp2f(x); }
; DI s16x4 vtr(const LAS unsigned char* p) { return __builtin_bit_cast(s16x4, __builtin_amdgcn_ds_read_tr16_b64_v4i16((LAS v4i16_t*)p)); }
; DI void flash_pv(FState& st, f32x16& p0, f32x16& p1, bool rowon, const LAS unsigned char* vb, int lane) {
;     ...
;     const float cl = rowon ? SM_C : 0.0f;
;     const float bl = rowon ? ((st.m == NINF) ? 0.0f : -st.m * SM_C) : NINF;
;     float sum = 0.f;
; #pragma unroll
;     for (int r = 0; r < 16; ++r) { p0[r] = fexp2(__builtin_fmaf(p0[r], cl, bl)); p1[r] = fexp2(__builtin_fmaf(p1[r], cl, bl)); sum += p0[r] + p1[r]; }
;     st.l += sum;
;     const int h = lane >> 5;
;     const int vx = (((lane & 15) >> 3) & 1) * 64;
;     const LAS unsigned char* vp = vb + (4 * h + ((lane & 15) >> 2)) * 128 + ((lane >> 4) & 1) * 32 + (lane & 3) * 8;
; #pragma unroll
;     for (int sub = 0; sub < 2; ++sub)
; #pragma unroll
;         for (int s2 = 0; s2 < 2; ++s2) {
;             const bf16x8 pf = pack8h(sub ? p1 : p0, s2);
;             const LAS unsigned char* vq = vp + (32 * sub + 16 * s2) * 128;
;             { const s16x4 lo = vtr(vq + vx), hi = vtr(vq + 1024 + vx); const bf16x8 vf = {lo[0], lo[1], lo[2], lo[3], hi[0], hi[1], hi[2], hi[3]}; st.o0 = MFMA32(vf, pf, st.o0); }
;             { const s16x4 lo = vtr(vq + (64 - vx)), hi = vtr(vq + 1024 + (64 - vx)); const bf16x8 vf = {lo[0], lo[1], lo[2], lo[3], hi[0], hi[1], hi[2], hi[3]}; st.o1 = MFMA32(vf, pf, st.o1); }
;         }
.Lnq_799:
	s_or_b64 exec, exec, s[4:5]
	v_fma_f32 v2, v130, v5, v4
	v_exp_f32_e32 v246, v2
	v_fma_f32 v2, v114, v5, v4
	v_exp_f32_e32 v247, v2
	s_waitcnt lgkmcnt(3)
	v_mfma_f32_32x32x16_bf16 v[98:113], v[226:229], v[154:157], v[98:113]
	v_fma_f32 v2, v131, v5, v4
	v_exp_f32_e32 v10, v2
	v_fma_f32 v2, v115, v5, v4
	v_exp_f32_e32 v2, v2
	v_add_f32_e32 v11, v246, v247
	v_pk_add_f32 v[6:7], v[10:11], v[2:3]
	s_nop 0
	v_pk_add_f32 v[130:131], v[6:7], v[6:7] op_sel_hi:[0,1]
	v_fma_f32 v6, v132, v5, v4
	v_exp_f32_e32 v11, v6
	s_waitcnt lgkmcnt(2)
	v_mfma_f32_32x32x16_bf16 v[82:97], v[230:233], v[154:157], v[82:97]
	v_fma_f32 v6, v116, v5, v4
	v_exp_f32_e32 v248, v6
	v_fma_f32 v6, v133, v5, v4
	v_exp_f32_e32 v12, v6
	v_fma_f32 v6, v117, v5, v4
	v_exp_f32_e32 v130, v6
	v_add_f32_e32 v13, v11, v248
	v_cvt_pk_bf16_f32 v10, v246, v10
	v_cvt_pk_bf16_f32 v11, v11, v12
	v_pk_add_f32 v[6:7], v[12:13], v[130:131]
	s_waitcnt lgkmcnt(1)
	v_mfma_f32_32x32x16_bf16 v[98:113], v[234:237], v[158:161], v[98:113]
	s_nop 0
	v_pk_add_f32 v[132:133], v[6:7], v[6:7] op_sel_hi:[0,1]
	v_fma_f32 v6, v134, v5, v4
	v_exp_f32_e32 v13, v6
	v_fma_f32 v6, v118, v5, v4
	v_exp_f32_e32 v131, v6
	v_fma_f32 v6, v135, v5, v4
	v_exp_f32_e32 v14, v6
	v_fma_f32 v6, v119, v5, v4
	v_exp_f32_e32 v132, v6
	s_waitcnt lgkmcnt(0)
	v_mfma_f32_32x32x16_bf16 v[82:97], v[238:241], v[158:161], v[82:97]
	v_add_f32_e32 v15, v13, v131
	v_cvt_pk_bf16_f32 v12, v13, v14
	v_pk_add_f32 v[6:7], v[14:15], v[132:133]
	s_nop 0
	v_pk_add_f32 v[118:119], v[6:7], v[6:7] op_sel_hi:[0,1]
	v_fma_f32 v6, v136, v5, v4
	v_exp_f32_e32 v15, v6
	v_fma_f32 v6, v120, v5, v4
	v_exp_f32_e32 v133, v6
	v_fma_f32 v6, v137, v5, v4
	v_exp_f32_e32 v16, v6
	v_fma_f32 v6, v121, v5, v4
	v_exp_f32_e32 v118, v6
	v_add_f32_e32 v17, v15, v133
	v_cvt_pk_bf16_f32 v13, v15, v16
	v_pk_add_f32 v[6:7], v[16:17], v[118:119]
	s_nop 0
	v_pk_add_f32 v[120:121], v[6:7], v[6:7] op_sel_hi:[0,1]
	v_fma_f32 v6, v138, v5, v4
	v_exp_f32_e32 v119, v6
	v_fma_f32 v6, v122, v5, v4
	v_exp_f32_e32 v249, v6
	v_fma_f32 v6, v139, v5, v4
	v_exp_f32_e32 v122, v6
	v_fma_f32 v6, v123, v5, v4
	v_exp_f32_e32 v120, v6
	v_fma_f32 v6, v140, v5, v4
	v_exp_f32_e32 v139, v6
	v_fma_f32 v6, v124, v5, v4
	v_add_f32_e32 v123, v119, v249
	v_exp_f32_e32 v140, v6
	v_pk_add_f32 v[6:7], v[122:123], v[120:121]
	v_fma_f32 v123, v144, v5, v4
	v_pk_add_f32 v[134:135], v[6:7], v[6:7] op_sel_hi:[0,1]
	v_fma_f32 v6, v141, v5, v4
	v_exp_f32_e32 v136, v6
	v_fma_f32 v6, v125, v5, v4
	v_exp_f32_e32 v134, v6
	ds_read_b64_tr_b16 v[6:7], v218 offset:40960
	ds_read_b64_tr_b16 v[8:9], v218 offset:41984
	ds_read_b64_tr_b16 v[14:15], v217 offset:41024
	ds_read_b64_tr_b16 v[16:17], v217 offset:42048
	ds_read_b64_tr_b16 v[114:115], v218 offset:43008
	ds_read_b64_tr_b16 v[116:117], v218 offset:44032
	s_waitcnt lgkmcnt(4)
	v_mfma_f32_32x32x16_bf16 v[66:81], v[6:9], v[10:13], v[66:81]
	v_fma_f32 v6, v142, v5, v4
	v_exp_f32_e32 v121, v6
	v_fma_f32 v6, v143, v5, v4
	v_exp_f32_e32 v124, v6
	v_exp_f32_e32 v141, v123
	v_add_f32_e32 v137, v139, v140
	ds_read_b64_tr_b16 v[6:7], v217 offset:43072
	ds_read_b64_tr_b16 v[8:9], v217 offset:44096
	s_waitcnt lgkmcnt(4)
	v_mfma_f32_32x32x16_bf16 v[50:65], v[14:17], v[10:13], v[50:65]
	v_fma_f32 v10, v145, v5, v4
	v_exp_f32_e32 v138, v10
	v_cvt_pk_bf16_f32 v10, v119, v122
	v_cvt_pk_bf16_f32 v11, v139, v136
	v_cvt_pk_bf16_f32 v12, v121, v124
	v_cvt_pk_bf16_f32 v13, v141, v138
	v_pk_add_f32 v[14:15], v[136:137], v[134:135]
	s_waitcnt lgkmcnt(2)
	v_mfma_f32_32x32x16_bf16 v[66:81], v[114:117], v[10:13], v[66:81]
	v_add_f32_e64 v122, v14, v14
	v_add_f32_e64 v123, v14, v15
	v_fma_f32 v14, v126, v5, v4
	v_exp_f32_e32 v126, v14
	ds_read_b64_tr_b16 v[14:15], v218 offset:45056
	ds_read_b64_tr_b16 v[16:17], v218 offset:46080
	v_fma_f32 v114, v127, v5, v4
	v_exp_f32_e32 v122, v114
	v_add_f32_e32 v125, v121, v126
	s_waitcnt lgkmcnt(2)
	v_mfma_f32_32x32x16_bf16 v[50:65], v[6:9], v[10:13], v[50:65]
	v_cvt_pk_bf16_f32 v6, v247, v2
	v_cvt_pk_bf16_f32 v7, v248, v130
	v_cvt_pk_bf16_f32 v8, v131, v132
	v_cvt_pk_bf16_f32 v9, v133, v118
	ds_read_b64_tr_b16 v[10:11], v218 offset:47104
	ds_read_b64_tr_b16 v[12:13], v218 offset:48128
	v_pk_add_f32 v[114:115], v[124:125], v[122:123]
	v_fma_f32 v2, v128, v5, v4
	s_waitcnt lgkmcnt(2)
	v_mfma_f32_32x32x16_bf16 v[66:81], v[14:17], v[6:9], v[66:81]
	ds_read_b64_tr_b16 v[14:15], v217 offset:45120
	ds_read_b64_tr_b16 v[16:17], v217 offset:46144
	v_add_f32_e64 v118, v114, v114
	v_add_f32_e64 v119, v114, v115
	v_fmac_f32_e32 v4, v129, v5
	ds_read_b64_tr_b16 v[114:115], v217 offset:47168
	ds_read_b64_tr_b16 v[116:117], v217 offset:48192
	v_exp_f32_e32 v2, v2
	v_exp_f32_e32 v118, v4
	v_cvt_pk_bf16_f32 v4, v249, v120
	s_waitcnt lgkmcnt(2)
	v_mfma_f32_32x32x16_bf16 v[50:65], v[14:17], v[6:9], v[50:65]
	v_cvt_pk_bf16_f32 v5, v140, v134
	v_cvt_pk_bf16_f32 v6, v126, v122
	v_cvt_pk_bf16_f32 v7, v2, v118
	v_add_f32_e32 v139, v141, v2
	v_add_f32_e64 v8, v138, v118
	v_add_f32_e64 v9, v139, v119
	v_add_f32_e32 v2, v8, v9
	v_mfma_f32_32x32x16_bf16 v[66:81], v[10:13], v[4:7], v[66:81]
	v_add_f32_e32 v214, v214, v2
	s_waitcnt lgkmcnt(0)
	v_mfma_f32_32x32x16_bf16 v[50:65], v[114:117], v[4:7], v[50:65]
	s_add_i32 s52, s52, -3
	s_andn2_b64 vcc, exec, s[6:7]
	s_add_i32 s53, s53, 0xc000
	s_cbranch_vccz .LBB0_712
